# weight-conversion tiles with row gain (w_in, w_up): the 16 gain values of a tile requested together instead of one exposed round trip each
# speedup vs baseline: 1.0018x; 1.0018x over previous
; #define LAS __attribute__((address_space(3)))
; template <bool PERMUTE, bool BLOCKED = false>
; __device__ __forceinline__ void cvt_tile64(const float* W, int K, int N, bf16* WT, int ldo, const float* gk, LAS float* scr, int tile, int lane) {
;     const int nblk = N >> 6, kb = tile / nblk, nb = tile - kb * nblk, k0 = 64 * kb, n0 = 64 * nb;
;     const int lk = lane >> 4, ln = (lane & 15) * 4;
;     ...
;     {
;         f32x4 v[16];
; #pragma unroll
;         for (int i = 0; i < 16; ++i) v[i] = *(const f32x4*)(W + (size_t)(k0 + 4 * i + lk) * N + n0 + ln);
; #pragma unroll
;         for (int i = 0; i < 16; ++i) { const int kk = 4 * i + lk; const float g = gk ? gk[k0 + kk] : 1.0f; LAS float* d = scr + kk * 65 + ln;
;             d[0] = v[i][0] * g; d[1] = v[i][1] * g; d[2] = v[i][2] * g; d[3] = v[i][3] * g; }
;     }
;     ...
; #pragma unroll
;     for (int hh = 0; hh < 2; ++hh) {
;         f32x4 v[8];
; #pragma unroll
;         for (int i = 0; i < 8; ++i) v[i] = *(const f32x4*)(W + (size_t)(k0 + 32 * hh + 4 * i + lk) * N + n0 + ln);
; #pragma unroll
;         for (int i = 0; i < 8; ++i) { const int kk = 32 * hh + 4 * i + lk; const float g = gk ? gk[k0 + kk] : 1.0f; LAS float* d = scr + kk * 65 + ln;
;             d[0] = v[i][0] * g; d[1] = v[i][1] * g; d[2] = v[i][2] * g; d[3] = v[i][3] * g; }
;     }
.LBB0_12:
	s_mul_hi_i32 s0, s15, 0x38e38e39
	s_lshr_b32 s1, s0, 31
	s_ashr_i32 s17, s0, 5
	s_add_i32 s17, s17, s1
	s_mul_i32 s0, s17, 0xffffdc00
	s_add_i32 s12, s3, s0
	s_lshl_b32 s10, s17, 6
	s_ashr_i32 s13, s12, 31
	v_or_b32_e32 v50, s10, v44
	v_lshl_add_u64 v[52:53], s[12:13], 2, v[46:47]
	v_mad_i64_i32 v[0:1], s[0:1], v50, s14, v[52:53]
	v_or_b32_e32 v2, 4, v50
	v_mad_i64_i32 v[2:3], s[0:1], v2, s14, v[52:53]
	global_load_dwordx4 v[28:31], v[0:1], off
	global_load_dwordx4 v[24:27], v[2:3], off
	v_or_b32_e32 v0, 8, v50
	v_mad_i64_i32 v[0:1], s[0:1], v0, s14, v[52:53]
	v_or_b32_e32 v2, 12, v50
	v_mad_i64_i32 v[2:3], s[0:1], v2, s14, v[52:53]
	global_load_dwordx4 v[20:23], v[0:1], off
	global_load_dwordx4 v[16:19], v[2:3], off
	v_or_b32_e32 v0, 16, v50
	v_mad_i64_i32 v[0:1], s[0:1], v0, s14, v[52:53]
	v_or_b32_e32 v2, 20, v50
	v_mad_i64_i32 v[2:3], s[0:1], v2, s14, v[52:53]
	global_load_dwordx4 v[12:15], v[0:1], off
	global_load_dwordx4 v[8:11], v[2:3], off
	v_or_b32_e32 v0, 24, v50
	v_mad_i64_i32 v[32:33], s[0:1], v0, s14, v[52:53]
	v_or_b32_e32 v0, 28, v50
	v_mad_i64_i32 v[34:35], s[0:1], v0, s14, v[52:53]
	global_load_dwordx4 v[4:7], v[32:33], off
	global_load_dwordx4 v[0:3], v[34:35], off
	v_ashrrev_i32_e32 v51, 31, v50
	v_mov_b32_e32 v32, 1.0
	s_and_b64 vcc, exec, s[4:5]
	v_mov_b32_e32 v34, 1.0
	s_cbranch_vccnz .LBB0_14
	v_readlane_b32 s48, v253, 11
	v_readlane_b32 s50, v253, 13
	v_readlane_b32 s51, v253, 14
	s_ashr_i32 s11, s10, 31
	v_readlane_b32 s49, v253, 12
	v_lshl_add_u64 v[34:35], v[50:51], 2, s[50:51]
	global_load_dword v110, v[34:35], off offset:16
	global_load_dword v124, v[34:35], off offset:32
	global_load_dword v125, v[34:35], off offset:48
	global_load_dword v126, v[34:35], off offset:64
	global_load_dword v127, v[34:35], off offset:80
	global_load_dword v178, v[34:35], off offset:96
	global_load_dword v179, v[34:35], off offset:112
	global_load_dword v180, v[34:35], off offset:128
	global_load_dword v181, v[34:35], off offset:144
	global_load_dword v182, v[34:35], off offset:160
	global_load_dword v183, v[34:35], off offset:176
	global_load_dword v184, v[34:35], off offset:192
	global_load_dword v185, v[34:35], off offset:208
	global_load_dword v186, v[34:35], off offset:224
	global_load_dword v187, v[34:35], off offset:240
	global_load_dword v36, v[34:35], off
	s_waitcnt vmcnt(0)
	v_lshl_add_u64 v[34:35], s[10:11], 0, v[44:45]
	v_lshl_add_u64 v[34:35], v[34:35], 2, s[50:51]
	v_mov_b32_e32 v34, v110
	v_readlane_b32 s52, v253, 15
	v_readlane_b32 s53, v253, 16
	v_readlane_b32 s54, v253, 17
	v_readlane_b32 s55, v253, 18
	v_readlane_b32 s56, v253, 19
	v_readlane_b32 s57, v253, 20
	v_readlane_b32 s58, v253, 21
	v_readlane_b32 s59, v253, 22
	v_readlane_b32 s60, v253, 23
	v_readlane_b32 s61, v253, 24
	v_readlane_b32 s62, v253, 25
	v_readlane_b32 s63, v253, 26
	s_waitcnt vmcnt(1)
	v_pk_mul_f32 v[28:29], v[28:29], v[36:37] op_sel_hi:[1,0]
	v_pk_mul_f32 v[30:31], v[30:31], v[36:37] op_sel_hi:[1,0]
.LBB0_14:
	s_waitcnt vmcnt(7)
	ds_write2_b32 v63, v28, v29 offset1:1
	ds_write2_b32 v63, v30, v31 offset0:2 offset1:3
	s_waitcnt vmcnt(0)
	v_pk_mul_f32 v[24:25], v[24:25], v[34:35] op_sel_hi:[1,0]
	v_add_u32_e32 v28, 0x410, v63
	ds_write2_b32 v28, v24, v25 offset1:1
	v_pk_mul_f32 v[24:25], v[26:27], v[34:35] op_sel_hi:[1,0]
	v_add_u32_e32 v26, 0x418, v63
	s_and_b64 vcc, exec, s[4:5]
	ds_write2_b32 v26, v24, v25 offset1:1
	s_cbranch_vccnz .LBB0_16
	s_ashr_i32 s11, s10, 31
	v_readlane_b32 s48, v253, 11
	v_lshl_add_u64 v[24:25], s[10:11], 0, v[44:45]
	v_readlane_b32 s50, v253, 13
	v_readlane_b32 s51, v253, 14
	v_readlane_b32 s49, v253, 12
	v_readlane_b32 s52, v253, 15
	v_lshl_add_u64 v[24:25], v[24:25], 2, s[50:51]
	v_mov_b32_e32 v26, v124
	v_mov_b32_e32 v32, v125
	v_readlane_b32 s53, v253, 16
	v_readlane_b32 s54, v253, 17
	v_readlane_b32 s55, v253, 18
	v_readlane_b32 s56, v253, 19
	v_readlane_b32 s57, v253, 20
	v_readlane_b32 s58, v253, 21
	v_readlane_b32 s59, v253, 22
	v_readlane_b32 s60, v253, 23
	v_readlane_b32 s61, v253, 24
	v_readlane_b32 s62, v253, 25
	v_readlane_b32 s63, v253, 26
	s_waitcnt vmcnt(1)
	v_pk_mul_f32 v[20:21], v[20:21], v[26:27] op_sel_hi:[1,0]
	v_pk_mul_f32 v[22:23], v[22:23], v[26:27] op_sel_hi:[1,0]
.LBB0_16:
	v_add_u32_e32 v24, 0x820, v63
	ds_write2_b32 v24, v20, v21 offset1:1
	v_add_u32_e32 v20, 0x828, v63
	ds_write2_b32 v20, v22, v23 offset1:1
	s_waitcnt vmcnt(0)
	v_pk_mul_f32 v[16:17], v[16:17], v[32:33] op_sel_hi:[1,0]
	v_add_u32_e32 v20, 0xc30, v63
	ds_write2_b32 v20, v16, v17 offset1:1
	v_pk_mul_f32 v[16:17], v[18:19], v[32:33] op_sel_hi:[1,0]
	v_add_u32_e32 v18, 0xc38, v63
	ds_write2_b32 v18, v16, v17 offset1:1
	v_mov_b32_e32 v54, 1.0
	s_and_b64 vcc, exec, s[4:5]
	v_mov_b32_e32 v16, 1.0
	s_cbranch_vccnz .LBB0_18
	s_ashr_i32 s11, s10, 31
	v_readlane_b32 s48, v253, 11
	v_lshl_add_u64 v[16:17], s[10:11], 0, v[44:45]
	v_readlane_b32 s50, v253, 13
	v_readlane_b32 s51, v253, 14
	v_readlane_b32 s49, v253, 12
	v_readlane_b32 s52, v253, 15
	v_lshl_add_u64 v[18:19], v[16:17], 2, s[50:51]
	v_mov_b32_e32 v20, v126
	v_mov_b32_e32 v16, v127
	v_readlane_b32 s53, v253, 16
	v_readlane_b32 s54, v253, 17
	v_readlane_b32 s55, v253, 18
	v_readlane_b32 s56, v253, 19
	v_readlane_b32 s57, v253, 20
	v_readlane_b32 s58, v253, 21
	v_readlane_b32 s59, v253, 22
	v_readlane_b32 s60, v253, 23
	v_readlane_b32 s61, v253, 24
	v_readlane_b32 s62, v253, 25
	v_readlane_b32 s63, v253, 26
	s_waitcnt vmcnt(1)
	v_pk_mul_f32 v[12:13], v[12:13], v[20:21] op_sel_hi:[1,0]
	v_pk_mul_f32 v[14:15], v[14:15], v[20:21] op_sel_hi:[1,0]
; #define LAS __attribute__((address_space(3)))
; template <bool PERMUTE, bool BLOCKED = false>
; __device__ __forceinline__ void cvt_tile64(const float* W, int K, int N, bf16* WT, int ldo, const float* gk, LAS float* scr, int tile, int lane) {
;     ...
; #pragma unroll
;     for (int hh = 0; hh < 2; ++hh) {
;         f32x4 v[8];
; #pragma unroll
;         for (int i = 0; i < 8; ++i) v[i] = *(const f32x4*)(W + (size_t)(k0 + 32 * hh + 4 * i + lk) * N + n0 + ln);
; #pragma unroll
;         for (int i = 0; i < 8; ++i) { const int kk = 32 * hh + 4 * i + lk; const float g = gk ? gk[k0 + kk] : 1.0f; LAS float* d = scr + kk * 65 + ln;
;             d[0] = v[i][0] * g; d[1] = v[i][1] * g; d[2] = v[i][2] * g; d[3] = v[i][3] * g; }
;     }
.LBB0_18:
	v_add_u32_e32 v17, 0x1040, v63
	ds_write2_b32 v17, v12, v13 offset1:1
	v_add_u32_e32 v12, 0x1048, v63
	ds_write2_b32 v12, v14, v15 offset1:1
	s_waitcnt vmcnt(0)
	v_pk_mul_f32 v[8:9], v[8:9], v[16:17] op_sel_hi:[1,0]
	v_add_u32_e32 v12, 0x1450, v63
	ds_write2_b32 v12, v8, v9 offset1:1
	v_pk_mul_f32 v[8:9], v[10:11], v[16:17] op_sel_hi:[1,0]
	v_add_u32_e32 v10, 0x1458, v63
	s_and_b64 vcc, exec, s[4:5]
	ds_write2_b32 v10, v8, v9 offset1:1
	s_cbranch_vccnz .LBB0_20
	s_ashr_i32 s11, s10, 31
	v_readlane_b32 s48, v253, 11
	v_lshl_add_u64 v[8:9], s[10:11], 0, v[44:45]
	v_readlane_b32 s50, v253, 13
	v_readlane_b32 s51, v253, 14
	v_readlane_b32 s49, v253, 12
	v_readlane_b32 s52, v253, 15
	v_lshl_add_u64 v[8:9], v[8:9], 2, s[50:51]
	v_mov_b32_e32 v10, v178
	v_mov_b32_e32 v54, v179
	v_readlane_b32 s53, v253, 16
	v_readlane_b32 s54, v253, 17
	v_readlane_b32 s55, v253, 18
	v_readlane_b32 s56, v253, 19
	v_readlane_b32 s57, v253, 20
	v_readlane_b32 s58, v253, 21
	v_readlane_b32 s59, v253, 22
	v_readlane_b32 s60, v253, 23
	v_readlane_b32 s61, v253, 24
	v_readlane_b32 s62, v253, 25
	v_readlane_b32 s63, v253, 26
	s_waitcnt vmcnt(1)
	v_pk_mul_f32 v[4:5], v[4:5], v[10:11] op_sel_hi:[1,0]
	v_pk_mul_f32 v[6:7], v[6:7], v[10:11] op_sel_hi:[1,0]
.LBB0_20:
	v_or_b32_e32 v8, 32, v50
	v_mad_i64_i32 v[8:9], s[0:1], v8, s14, v[52:53]
	v_or_b32_e32 v10, 36, v50
	v_mad_i64_i32 v[10:11], s[0:1], v10, s14, v[52:53]
	global_load_dwordx4 v[36:39], v[8:9], off
	global_load_dwordx4 v[32:35], v[10:11], off
	v_or_b32_e32 v8, 40, v50
	v_mad_i64_i32 v[8:9], s[0:1], v8, s14, v[52:53]
	v_or_b32_e32 v10, 44, v50
	v_mad_i64_i32 v[10:11], s[0:1], v10, s14, v[52:53]
	global_load_dwordx4 v[28:31], v[8:9], off
	global_load_dwordx4 v[24:27], v[10:11], off
	v_or_b32_e32 v8, 48, v50
	v_mad_i64_i32 v[8:9], s[0:1], v8, s14, v[52:53]
	v_or_b32_e32 v10, 52, v50
	v_mad_i64_i32 v[10:11], s[0:1], v10, s14, v[52:53]
	global_load_dwordx4 v[20:23], v[8:9], off
	global_load_dwordx4 v[16:19], v[10:11], off
	v_or_b32_e32 v8, 56, v50
	v_mad_i64_i32 v[64:65], s[0:1], v8, s14, v[52:53]
	v_or_b32_e32 v8, 60, v50
	v_mad_i64_i32 v[50:51], s[0:1], v8, s14, v[52:53]
	global_load_dwordx4 v[12:15], v[64:65], off
	global_load_dwordx4 v[8:11], v[50:51], off
	v_add_u32_e32 v50, 0x1860, v63
	ds_write2_b32 v50, v4, v5 offset1:1
	v_add_u32_e32 v4, 0x1868, v63
	ds_write2_b32 v4, v6, v7 offset1:1
	s_waitcnt vmcnt(8)
	v_pk_mul_f32 v[0:1], v[0:1], v[54:55] op_sel_hi:[1,0]
	v_add_u32_e32 v4, 0x1c70, v63
	ds_write2_b32 v4, v0, v1 offset1:1
	v_pk_mul_f32 v[0:1], v[2:3], v[54:55] op_sel_hi:[1,0]
	v_add_u32_e32 v2, 0x1c78, v63
	ds_write2_b32 v2, v0, v1 offset1:1
	v_mov_b32_e32 v0, 1.0
	s_and_b64 vcc, exec, s[4:5]
	v_mov_b32_e32 v2, 1.0
	s_cbranch_vccnz .LBB0_22
	s_ashr_i32 s11, s10, 31
	v_readlane_b32 s48, v253, 11
	v_lshl_add_u64 v[2:3], s[10:11], 0, v[44:45]
	v_readlane_b32 s50, v253, 13
	v_readlane_b32 s51, v253, 14
	v_readlane_b32 s49, v253, 12
	v_readlane_b32 s52, v253, 15
	v_lshl_add_u64 v[4:5], v[2:3], 2, s[50:51]
	v_mov_b32_e32 v6, v180
	v_mov_b32_e32 v2, v181
	v_readlane_b32 s53, v253, 16
	v_readlane_b32 s54, v253, 17
	v_readlane_b32 s55, v253, 18
	v_readlane_b32 s56, v253, 19
	v_readlane_b32 s57, v253, 20
	v_readlane_b32 s58, v253, 21
	v_readlane_b32 s59, v253, 22
	v_readlane_b32 s60, v253, 23
	v_readlane_b32 s61, v253, 24
	v_readlane_b32 s62, v253, 25
	v_readlane_b32 s63, v253, 26
	s_waitcnt vmcnt(1)
	v_pk_mul_f32 v[36:37], v[36:37], v[6:7] op_sel_hi:[1,0]
	v_pk_mul_f32 v[38:39], v[38:39], v[6:7] op_sel_hi:[1,0]
.LBB0_22:
	v_add_u32_e32 v1, 0x2080, v63
	s_waitcnt vmcnt(7)
	ds_write2_b32 v1, v36, v37 offset1:1
	v_add_u32_e32 v1, 0x2088, v63
	ds_write2_b32 v1, v38, v39 offset1:1
	s_waitcnt vmcnt(0)
	v_pk_mul_f32 v[4:5], v[32:33], v[2:3] op_sel_hi:[1,0]
	v_add_u32_e32 v1, 0x2490, v63
	ds_write2_b32 v1, v4, v5 offset1:1
	v_pk_mul_f32 v[2:3], v[34:35], v[2:3] op_sel_hi:[1,0]
	v_add_u32_e32 v1, 0x2498, v63
	s_and_b64 vcc, exec, s[4:5]
	ds_write2_b32 v1, v2, v3 offset1:1
	s_cbranch_vccnz .LBB0_24
	s_ashr_i32 s11, s10, 31
	v_readlane_b32 s48, v253, 11
	v_lshl_add_u64 v[0:1], s[10:11], 0, v[44:45]
	v_readlane_b32 s50, v253, 13
	v_readlane_b32 s51, v253, 14
	v_readlane_b32 s49, v253, 12
	v_readlane_b32 s52, v253, 15
	v_lshl_add_u64 v[2:3], v[0:1], 2, s[50:51]
	v_mov_b32_e32 v4, v182
	v_mov_b32_e32 v0, v183
	v_readlane_b32 s53, v253, 16
	v_readlane_b32 s54, v253, 17
	v_readlane_b32 s55, v253, 18
	v_readlane_b32 s56, v253, 19
	v_readlane_b32 s57, v253, 20
	v_readlane_b32 s58, v253, 21
	v_readlane_b32 s59, v253, 22
	v_readlane_b32 s60, v253, 23
	v_readlane_b32 s61, v253, 24
	v_readlane_b32 s62, v253, 25
	v_readlane_b32 s63, v253, 26
	s_waitcnt vmcnt(1)
	v_pk_mul_f32 v[28:29], v[28:29], v[4:5] op_sel_hi:[1,0]
	v_pk_mul_f32 v[30:31], v[30:31], v[4:5] op_sel_hi:[1,0]
.LBB0_24:
	v_add_u32_e32 v1, 0x28a0, v63
	ds_write2_b32 v1, v28, v29 offset1:1
	v_add_u32_e32 v1, 0x28a8, v63
	ds_write2_b32 v1, v30, v31 offset1:1
	s_waitcnt vmcnt(0)
	v_pk_mul_f32 v[2:3], v[24:25], v[0:1] op_sel_hi:[1,0]
	v_add_u32_e32 v1, 0x2cb0, v63
	ds_write2_b32 v1, v2, v3 offset1:1
	v_pk_mul_f32 v[0:1], v[26:27], v[0:1] op_sel_hi:[1,0]
	v_add_u32_e32 v2, 0x2cb8, v63
	s_and_b64 vcc, exec, s[4:5]
	ds_write2_b32 v2, v0, v1 offset1:1
	s_cbranch_vccnz .LBB0_26
	s_ashr_i32 s11, s10, 31
	v_readlane_b32 s48, v253, 11
	v_lshl_add_u64 v[0:1], s[10:11], 0, v[44:45]
	v_readlane_b32 s50, v253, 13
	v_readlane_b32 s51, v253, 14
	v_readlane_b32 s49, v253, 12
	v_readlane_b32 s52, v253, 15
	v_lshl_add_u64 v[2:3], v[0:1], 2, s[50:51]
	v_mov_b32_e32 v4, v184
	v_mov_b32_e32 v0, v185
	v_readlane_b32 s53, v253, 16
	v_readlane_b32 s54, v253, 17
	v_readlane_b32 s55, v253, 18
	v_readlane_b32 s56, v253, 19
	v_readlane_b32 s57, v253, 20
	v_readlane_b32 s58, v253, 21
	v_readlane_b32 s59, v253, 22
	v_readlane_b32 s60, v253, 23
	v_readlane_b32 s61, v253, 24
	v_readlane_b32 s62, v253, 25
	v_readlane_b32 s63, v253, 26
	s_waitcnt vmcnt(1)
	v_pk_mul_f32 v[20:21], v[20:21], v[4:5] op_sel_hi:[1,0]
	v_pk_mul_f32 v[22:23], v[22:23], v[4:5] op_sel_hi:[1,0]
	s_branch .LBB0_27

; #define LAS __attribute__((address_space(3)))
; template <bool PERMUTE, bool BLOCKED = false>
; __device__ __forceinline__ void cvt_tile64(const float* W, int K, int N, bf16* WT, int ldo, const float* gk, LAS float* scr, int tile, int lane) {
;     ...
;         for (int i = 0; i < 8; ++i) { const int kk = 32 * hh + 4 * i + lk; const float g = gk ? gk[k0 + kk] : 1.0f; LAS float* d = scr + kk * 65 + ln;
;             d[0] = v[i][0] * g; d[1] = v[i][1] * g; d[2] = v[i][2] * g; d[3] = v[i][3] * g; }
;     }
.LBB0_27:
	v_add_u32_e32 v1, 0x30c0, v63
	ds_write2_b32 v1, v20, v21 offset1:1
	v_add_u32_e32 v1, 0x30c8, v63
	ds_write2_b32 v1, v22, v23 offset1:1
	s_waitcnt vmcnt(0)
	v_pk_mul_f32 v[2:3], v[16:17], v[0:1] op_sel_hi:[1,0]
	v_add_u32_e32 v1, 0x34d0, v63
	ds_write2_b32 v1, v2, v3 offset1:1
	v_pk_mul_f32 v[0:1], v[18:19], v[0:1] op_sel_hi:[1,0]
	v_add_u32_e32 v2, 0x34d8, v63
	s_and_b64 vcc, exec, s[6:7]
	ds_write2_b32 v2, v0, v1 offset1:1
	s_cbranch_vccz .LBB0_29
	s_ashr_i32 s11, s10, 31
	v_readlane_b32 s48, v253, 11
	v_lshl_add_u64 v[0:1], s[10:11], 0, v[44:45]
	v_readlane_b32 s50, v253, 13
	v_readlane_b32 s51, v253, 14
	v_readlane_b32 s49, v253, 12
	v_readlane_b32 s52, v253, 15
	v_lshl_add_u64 v[2:3], v[0:1], 2, s[50:51]
	v_mov_b32_e32 v4, v186
	v_mov_b32_e32 v0, v187
	v_readlane_b32 s53, v253, 16
	v_readlane_b32 s54, v253, 17
	v_readlane_b32 s55, v253, 18
	v_readlane_b32 s56, v253, 19
	v_readlane_b32 s57, v253, 20
	v_readlane_b32 s58, v253, 21
	v_readlane_b32 s59, v253, 22
	v_readlane_b32 s60, v253, 23
	v_readlane_b32 s61, v253, 24
	v_readlane_b32 s62, v253, 25
	v_readlane_b32 s63, v253, 26
	s_waitcnt vmcnt(1)
	v_pk_mul_f32 v[12:13], v[12:13], v[4:5] op_sel_hi:[1,0]
	v_pk_mul_f32 v[14:15], v[14:15], v[4:5] op_sel_hi:[1,0]
	s_cbranch_execnz .LBB0_11
	s_branch .LBB0_30

; #define LAS __attribute__((address_space(3)))
; template <bool PERMUTE, bool BLOCKED = false>
; __device__ __forceinline__ void cvt_tile64(const float* W, int K, int N, bf16* WT, int ldo, const float* gk, LAS float* scr, int tile, int lane) {
;     const int nblk = N >> 6, kb = tile / nblk, nb = tile - kb * nblk, k0 = 64 * kb, n0 = 64 * nb;
;     const int lk = lane >> 4, ln = (lane & 15) * 4;
;     ...
;     {
;         f32x4 v[16];
; #pragma unroll
;         for (int i = 0; i < 16; ++i) v[i] = *(const f32x4*)(W + (size_t)(k0 + 4 * i + lk) * N + n0 + ln);
; #pragma unroll
;         for (int i = 0; i < 16; ++i) { const int kk = 4 * i + lk; const float g = gk ? gk[k0 + kk] : 1.0f; LAS float* d = scr + kk * 65 + ln;
;             d[0] = v[i][0] * g; d[1] = v[i][1] * g; d[2] = v[i][2] * g; d[3] = v[i][3] * g; }
;     }
;     ...
; #pragma unroll
;     for (int hh = 0; hh < 2; ++hh) {
;         f32x4 v[8];
; #pragma unroll
;         for (int i = 0; i < 8; ++i) v[i] = *(const f32x4*)(W + (size_t)(k0 + 32 * hh + 4 * i + lk) * N + n0 + ln);
; #pragma unroll
;         for (int i = 0; i < 8; ++i) { const int kk = 32 * hh + 4 * i + lk; const float g = gk ? gk[k0 + kk] : 1.0f; LAS float* d = scr + kk * 65 + ln;
;             d[0] = v[i][0] * g; d[1] = v[i][1] * g; d[2] = v[i][2] * g; d[3] = v[i][3] * g; }
;     }
; __device__ __forceinline__ void cvt_item(const CvtCtx& c, int batch, int wi, LAS float* scr, int wave, int lane) {
;     ...
;     if (wi < CVT_OUT) { cvt_tile64<false>(c.w_out + (size_t)l * DM * DM, DM, DM, c.WoutT + (size_t)l * DM * DM, DM, nullptr, scr, 8 * wi + wave, lane); return; } wi -= CVT_OUT;
;     if (wi < CVT_UP) { cvt_tile64<false>(c.w_up + (size_t)l * DM * DFF, DM, DFF, c.WupT + (size_t)l * DFF * DM, DM, c.g_mlp + l * DM, scr, 8 * wi + wave, lane); return; } wi -= CVT_UP;
.LBB0_94:
	s_cmpk_gt_i32 s14, 0x1ff
	s_mov_b64 s[0:1], -1
	s_cbranch_scc0 .LBB0_114
	s_add_i32 s0, s5, 0xfffff000
	s_ashr_i32 s1, s0, 31
	s_lshr_b32 s1, s1, 24
	s_add_i32 s0, s0, s1
	s_ashr_i32 s0, s0, 8
	s_lshl_b32 s12, s0, 6
	s_lshl_b32 s15, s0, 14
	s_sub_i32 s0, s4, s15
	v_or_b32_e32 v52, s12, v16
	s_add_i32 s0, s0, 0xfffc0000
	v_or_b32_e32 v2, 4, v52
	s_ashr_i32 s1, s0, 31
	v_ashrrev_i32_e32 v53, 31, v52
	v_ashrrev_i32_e32 v3, 31, v2
	v_lshl_add_u64 v[50:51], s[0:1], 2, v[42:43]
	v_lshlrev_b64 v[0:1], 16, v[52:53]
	v_lshlrev_b64 v[2:3], 16, v[2:3]
	v_lshl_add_u64 v[0:1], v[50:51], 0, v[0:1]
	v_lshl_add_u64 v[2:3], v[50:51], 0, v[2:3]
	global_load_dwordx4 v[30:33], v[0:1], off
	global_load_dwordx4 v[26:29], v[2:3], off
	v_or_b32_e32 v0, 8, v52
	v_or_b32_e32 v2, 12, v52
	v_ashrrev_i32_e32 v1, 31, v0
	v_ashrrev_i32_e32 v3, 31, v2
	v_lshlrev_b64 v[0:1], 16, v[0:1]
	v_lshlrev_b64 v[2:3], 16, v[2:3]
	v_lshl_add_u64 v[0:1], v[50:51], 0, v[0:1]
	v_lshl_add_u64 v[2:3], v[50:51], 0, v[2:3]
	global_load_dwordx4 v[22:25], v[0:1], off
	global_load_dwordx4 v[18:21], v[2:3], off
	v_or_b32_e32 v0, 16, v52
	v_or_b32_e32 v2, 20, v52
	v_ashrrev_i32_e32 v1, 31, v0
	v_ashrrev_i32_e32 v3, 31, v2
	v_lshlrev_b64 v[0:1], 16, v[0:1]
	v_lshlrev_b64 v[2:3], 16, v[2:3]
	v_lshl_add_u64 v[0:1], v[50:51], 0, v[0:1]
	v_lshl_add_u64 v[2:3], v[50:51], 0, v[2:3]
	global_load_dwordx4 v[12:15], v[0:1], off
	global_load_dwordx4 v[8:11], v[2:3], off
	v_or_b32_e32 v0, 24, v52
	v_or_b32_e32 v2, 28, v52
	v_ashrrev_i32_e32 v1, 31, v0
	v_ashrrev_i32_e32 v3, 31, v2
	v_lshlrev_b64 v[0:1], 16, v[0:1]
	v_lshlrev_b64 v[2:3], 16, v[2:3]
	v_lshl_add_u64 v[0:1], v[50:51], 0, v[0:1]
	v_lshl_add_u64 v[2:3], v[50:51], 0, v[2:3]
	global_load_dwordx4 v[4:7], v[0:1], off
	s_nop 0
	global_load_dwordx4 v[0:3], v[2:3], off
	v_cmp_ne_u32_e64 s[6:7], 1, v59
	s_andn2_b64 vcc, exec, s[10:11]
	v_mov_b32_e32 v34, 1.0
	v_mov_b32_e32 v36, 1.0
	s_cbranch_vccnz .LBB0_97
	v_lshl_add_u64 v[36:37], v[52:53], 2, s[8:9]
	s_ashr_i32 s13, s12, 31
	global_load_dword v110, v[36:37], off offset:16
	global_load_dword v124, v[36:37], off offset:32
	global_load_dword v125, v[36:37], off offset:48
	global_load_dword v126, v[36:37], off offset:64
	global_load_dword v127, v[36:37], off offset:80
	global_load_dword v178, v[36:37], off offset:96
	global_load_dword v179, v[36:37], off offset:112
	global_load_dword v180, v[36:37], off offset:128
	global_load_dword v181, v[36:37], off offset:144
	global_load_dword v182, v[36:37], off offset:160
	global_load_dword v183, v[36:37], off offset:176
	global_load_dword v184, v[36:37], off offset:192
	global_load_dword v185, v[36:37], off offset:208
	global_load_dword v186, v[36:37], off offset:224
	global_load_dword v187, v[36:37], off offset:240
	global_load_dword v38, v[36:37], off
	s_waitcnt vmcnt(0)
	v_lshl_add_u64 v[36:37], s[12:13], 0, v[16:17]
	v_lshl_add_u64 v[36:37], v[36:37], 2, s[8:9]
	v_mov_b32_e32 v36, v110
	s_waitcnt vmcnt(1)
	v_pk_mul_f32 v[30:31], v[30:31], v[38:39] op_sel_hi:[1,0]
	v_pk_mul_f32 v[32:33], v[32:33], v[38:39] op_sel_hi:[1,0]
.LBB0_97:
	v_add_u32_e32 v53, v55, v56
	s_waitcnt vmcnt(7)
	ds_write2_b32 v53, v30, v31 offset1:1
	ds_write2_b32 v53, v32, v33 offset0:2 offset1:3
	s_waitcnt vmcnt(0)
	v_pk_mul_f32 v[26:27], v[26:27], v[36:37] op_sel_hi:[1,0]
	v_add_u32_e32 v30, 0x410, v53
	ds_write2_b32 v30, v26, v27 offset1:1
	v_pk_mul_f32 v[26:27], v[28:29], v[36:37] op_sel_hi:[1,0]
	v_add_u32_e32 v28, 0x418, v53
	s_and_b64 vcc, exec, s[6:7]
	ds_write2_b32 v28, v26, v27 offset1:1
	s_cbranch_vccnz .LBB0_99
	s_ashr_i32 s13, s12, 31
	v_lshl_add_u64 v[26:27], s[12:13], 0, v[16:17]
	v_lshl_add_u64 v[26:27], v[26:27], 2, s[8:9]
	v_mov_b32_e32 v28, v124
	v_mov_b32_e32 v34, v125
	s_waitcnt vmcnt(1)
	v_pk_mul_f32 v[22:23], v[22:23], v[28:29] op_sel_hi:[1,0]
	v_pk_mul_f32 v[24:25], v[24:25], v[28:29] op_sel_hi:[1,0]
.LBB0_99:
	v_add_u32_e32 v26, 0x820, v53
	ds_write2_b32 v26, v22, v23 offset1:1
	v_add_u32_e32 v22, 0x828, v53
	ds_write2_b32 v22, v24, v25 offset1:1
	s_waitcnt vmcnt(0)
	v_pk_mul_f32 v[18:19], v[18:19], v[34:35] op_sel_hi:[1,0]
	v_add_u32_e32 v22, 0xc30, v53
	ds_write2_b32 v22, v18, v19 offset1:1
	v_pk_mul_f32 v[18:19], v[20:21], v[34:35] op_sel_hi:[1,0]
	v_add_u32_e32 v20, 0xc38, v53
	ds_write2_b32 v20, v18, v19 offset1:1
	v_mov_b32_e32 v54, 1.0
	s_and_b64 vcc, exec, s[6:7]
	v_mov_b32_e32 v18, 1.0
	s_cbranch_vccnz .LBB0_101
	s_ashr_i32 s13, s12, 31
	v_lshl_add_u64 v[18:19], s[12:13], 0, v[16:17]
	v_lshl_add_u64 v[18:19], v[18:19], 2, s[8:9]
	v_mov_b32_e32 v20, v126
	s_nop 0
	v_mov_b32_e32 v18, v127
	s_waitcnt vmcnt(1)
	v_pk_mul_f32 v[12:13], v[12:13], v[20:21] op_sel_hi:[1,0]
	v_pk_mul_f32 v[14:15], v[14:15], v[20:21] op_sel_hi:[1,0]
; #define LAS __attribute__((address_space(3)))
; template <bool PERMUTE, bool BLOCKED = false>
; __device__ __forceinline__ void cvt_tile64(const float* W, int K, int N, bf16* WT, int ldo, const float* gk, LAS float* scr, int tile, int lane) {
;     ...
; #pragma unroll
;     for (int hh = 0; hh < 2; ++hh) {
;         f32x4 v[8];
; #pragma unroll
;         for (int i = 0; i < 8; ++i) v[i] = *(const f32x4*)(W + (size_t)(k0 + 32 * hh + 4 * i + lk) * N + n0 + ln);
; #pragma unroll
;         for (int i = 0; i < 8; ++i) { const int kk = 32 * hh + 4 * i + lk; const float g = gk ? gk[k0 + kk] : 1.0f; LAS float* d = scr + kk * 65 + ln;
;             d[0] = v[i][0] * g; d[1] = v[i][1] * g; d[2] = v[i][2] * g; d[3] = v[i][3] * g; }
;     }
.LBB0_101:
	v_add_u32_e32 v19, 0x1040, v53
	ds_write2_b32 v19, v12, v13 offset1:1
	v_add_u32_e32 v12, 0x1048, v53
	ds_write2_b32 v12, v14, v15 offset1:1
	s_waitcnt vmcnt(0)
	v_pk_mul_f32 v[8:9], v[8:9], v[18:19] op_sel_hi:[1,0]
	v_add_u32_e32 v12, 0x1450, v53
	ds_write2_b32 v12, v8, v9 offset1:1
	v_pk_mul_f32 v[8:9], v[10:11], v[18:19] op_sel_hi:[1,0]
	v_add_u32_e32 v10, 0x1458, v53
	s_and_b64 vcc, exec, s[6:7]
	ds_write2_b32 v10, v8, v9 offset1:1
	s_cbranch_vccnz .LBB0_103
	s_ashr_i32 s13, s12, 31
	v_lshl_add_u64 v[8:9], s[12:13], 0, v[16:17]
	v_lshl_add_u64 v[8:9], v[8:9], 2, s[8:9]
	v_mov_b32_e32 v10, v178
	v_mov_b32_e32 v54, v179
	s_waitcnt vmcnt(1)
	v_pk_mul_f32 v[4:5], v[4:5], v[10:11] op_sel_hi:[1,0]
	v_pk_mul_f32 v[6:7], v[6:7], v[10:11] op_sel_hi:[1,0]
.LBB0_103:
	v_or_b32_e32 v8, 32, v52
	v_or_b32_e32 v10, 36, v52
	v_ashrrev_i32_e32 v9, 31, v8
	v_ashrrev_i32_e32 v11, 31, v10
	v_lshlrev_b64 v[8:9], 16, v[8:9]
	v_lshlrev_b64 v[10:11], 16, v[10:11]
	v_lshl_add_u64 v[8:9], v[50:51], 0, v[8:9]
	v_lshl_add_u64 v[10:11], v[50:51], 0, v[10:11]
	global_load_dwordx4 v[38:41], v[8:9], off
	global_load_dwordx4 v[34:37], v[10:11], off
	v_or_b32_e32 v8, 40, v52
	v_or_b32_e32 v10, 44, v52
	v_ashrrev_i32_e32 v9, 31, v8
	v_ashrrev_i32_e32 v11, 31, v10
	v_lshlrev_b64 v[8:9], 16, v[8:9]
	v_lshlrev_b64 v[10:11], 16, v[10:11]
	v_lshl_add_u64 v[8:9], v[50:51], 0, v[8:9]
	v_lshl_add_u64 v[10:11], v[50:51], 0, v[10:11]
	global_load_dwordx4 v[30:33], v[8:9], off
	global_load_dwordx4 v[26:29], v[10:11], off
	v_or_b32_e32 v8, 48, v52
	v_or_b32_e32 v10, 52, v52
	v_ashrrev_i32_e32 v9, 31, v8
	v_ashrrev_i32_e32 v11, 31, v10
	v_lshlrev_b64 v[8:9], 16, v[8:9]
	v_lshlrev_b64 v[10:11], 16, v[10:11]
	v_lshl_add_u64 v[8:9], v[50:51], 0, v[8:9]
	v_lshl_add_u64 v[10:11], v[50:51], 0, v[10:11]
	global_load_dwordx4 v[22:25], v[8:9], off
	global_load_dwordx4 v[18:21], v[10:11], off
	v_or_b32_e32 v8, 56, v52
	v_or_b32_e32 v10, 60, v52
	v_ashrrev_i32_e32 v9, 31, v8
	v_ashrrev_i32_e32 v11, 31, v10
	v_lshlrev_b64 v[8:9], 16, v[8:9]
	v_lshlrev_b64 v[10:11], 16, v[10:11]
	v_lshl_add_u64 v[8:9], v[50:51], 0, v[8:9]
	v_lshl_add_u64 v[10:11], v[50:51], 0, v[10:11]
	global_load_dwordx4 v[12:15], v[8:9], off
	s_nop 0
	global_load_dwordx4 v[8:11], v[10:11], off
	v_add_u32_e32 v50, 0x1860, v53
	ds_write2_b32 v50, v4, v5 offset1:1
	v_add_u32_e32 v4, 0x1868, v53
	ds_write2_b32 v4, v6, v7 offset1:1
	s_waitcnt vmcnt(8)
	v_pk_mul_f32 v[0:1], v[0:1], v[54:55] op_sel_hi:[1,0]
	v_add_u32_e32 v4, 0x1c70, v53
	ds_write2_b32 v4, v0, v1 offset1:1
	v_pk_mul_f32 v[0:1], v[2:3], v[54:55] op_sel_hi:[1,0]
	v_add_u32_e32 v2, 0x1c78, v53
	ds_write2_b32 v2, v0, v1 offset1:1
	v_mov_b32_e32 v0, 1.0
	s_and_b64 vcc, exec, s[6:7]
	v_mov_b32_e32 v2, 1.0
	s_cbranch_vccnz .LBB0_105
	s_ashr_i32 s13, s12, 31
	v_lshl_add_u64 v[2:3], s[12:13], 0, v[16:17]
	v_lshl_add_u64 v[2:3], v[2:3], 2, s[8:9]
	v_mov_b32_e32 v4, v180
	s_nop 0
	v_mov_b32_e32 v2, v181
	s_waitcnt vmcnt(1)
	v_pk_mul_f32 v[38:39], v[38:39], v[4:5] op_sel_hi:[1,0]
	v_pk_mul_f32 v[40:41], v[40:41], v[4:5] op_sel_hi:[1,0]
.LBB0_105:
	v_add_u32_e32 v1, 0x2080, v53
	s_waitcnt vmcnt(7)
	ds_write2_b32 v1, v38, v39 offset1:1
	v_add_u32_e32 v1, 0x2088, v53
	ds_write2_b32 v1, v40, v41 offset1:1
	s_waitcnt vmcnt(0)
	v_pk_mul_f32 v[4:5], v[34:35], v[2:3] op_sel_hi:[1,0]
	v_add_u32_e32 v1, 0x2490, v53
	ds_write2_b32 v1, v4, v5 offset1:1
	v_pk_mul_f32 v[2:3], v[36:37], v[2:3] op_sel_hi:[1,0]
	v_add_u32_e32 v1, 0x2498, v53
	s_and_b64 vcc, exec, s[6:7]
	ds_write2_b32 v1, v2, v3 offset1:1
	s_cbranch_vccnz .LBB0_107
	s_ashr_i32 s13, s12, 31
	v_lshl_add_u64 v[0:1], s[12:13], 0, v[16:17]
	v_lshl_add_u64 v[0:1], v[0:1], 2, s[8:9]
	v_mov_b32_e32 v2, v182
	s_nop 0
	v_mov_b32_e32 v0, v183
	s_waitcnt vmcnt(1)
	v_pk_mul_f32 v[30:31], v[30:31], v[2:3] op_sel_hi:[1,0]
	v_pk_mul_f32 v[32:33], v[32:33], v[2:3] op_sel_hi:[1,0]
.LBB0_107:
	v_add_u32_e32 v1, 0x28a0, v53
	ds_write2_b32 v1, v30, v31 offset1:1
	v_add_u32_e32 v1, 0x28a8, v53
	ds_write2_b32 v1, v32, v33 offset1:1
	s_waitcnt vmcnt(0)
	v_pk_mul_f32 v[2:3], v[26:27], v[0:1] op_sel_hi:[1,0]
	v_add_u32_e32 v1, 0x2cb0, v53
	ds_write2_b32 v1, v2, v3 offset1:1
	v_pk_mul_f32 v[0:1], v[28:29], v[0:1] op_sel_hi:[1,0]
	v_add_u32_e32 v2, 0x2cb8, v53
	s_and_b64 vcc, exec, s[6:7]
	ds_write2_b32 v2, v0, v1 offset1:1
	s_cbranch_vccnz .LBB0_109
	s_ashr_i32 s13, s12, 31
	v_lshl_add_u64 v[0:1], s[12:13], 0, v[16:17]
	v_lshl_add_u64 v[0:1], v[0:1], 2, s[8:9]
	v_mov_b32_e32 v2, v184
	s_nop 0
	v_mov_b32_e32 v0, v185
	s_waitcnt vmcnt(1)
	v_pk_mul_f32 v[22:23], v[22:23], v[2:3] op_sel_hi:[1,0]
	v_pk_mul_f32 v[24:25], v[24:25], v[2:3] op_sel_hi:[1,0]
	s_branch .LBB0_110

; #define LAS __attribute__((address_space(3)))
; template <bool PERMUTE, bool BLOCKED = false>
; __device__ __forceinline__ void cvt_tile64(const float* W, int K, int N, bf16* WT, int ldo, const float* gk, LAS float* scr, int tile, int lane) {
;     ...
;         for (int i = 0; i < 8; ++i) { const int kk = 32 * hh + 4 * i + lk; const float g = gk ? gk[k0 + kk] : 1.0f; LAS float* d = scr + kk * 65 + ln;
;             d[0] = v[i][0] * g; d[1] = v[i][1] * g; d[2] = v[i][2] * g; d[3] = v[i][3] * g; }
;     }
.LBB0_110:
	v_add_u32_e32 v1, 0x30c0, v53
	ds_write2_b32 v1, v22, v23 offset1:1
	v_add_u32_e32 v1, 0x30c8, v53
	ds_write2_b32 v1, v24, v25 offset1:1
	s_waitcnt vmcnt(0)
	v_pk_mul_f32 v[2:3], v[18:19], v[0:1] op_sel_hi:[1,0]
	v_add_u32_e32 v1, 0x34d0, v53
	ds_write2_b32 v1, v2, v3 offset1:1
	v_pk_mul_f32 v[0:1], v[20:21], v[0:1] op_sel_hi:[1,0]
	v_add_u32_e32 v2, 0x34d8, v53
	s_and_b64 vcc, exec, s[10:11]
	ds_write2_b32 v2, v0, v1 offset1:1
	s_cbranch_vccz .LBB0_116
	s_ashr_i32 s13, s12, 31
	v_lshl_add_u64 v[0:1], s[12:13], 0, v[16:17]
	v_lshl_add_u64 v[0:1], v[0:1], 2, s[8:9]
	v_mov_b32_e32 v2, v186
	s_nop 0
	v_mov_b32_e32 v0, v187
	s_waitcnt vmcnt(1)
	v_pk_mul_f32 v[12:13], v[12:13], v[2:3] op_sel_hi:[1,0]
	v_pk_mul_f32 v[14:15], v[14:15], v[2:3] op_sel_hi:[1,0]
	s_cbranch_execnz .LBB0_113

; #define LAS __attribute__((address_space(3)))
; template <bool PERMUTE, bool BLOCKED = false>
; __device__ __forceinline__ void cvt_tile64(const float* W, int K, int N, bf16* WT, int ldo, const float* gk, LAS float* scr, int tile, int lane) {
;     const int nblk = N >> 6, kb = tile / nblk, nb = tile - kb * nblk, k0 = 64 * kb, n0 = 64 * nb;
;     const int lk = lane >> 4, ln = (lane & 15) * 4;
;     ...
;     {
;         f32x4 v[16];
; #pragma unroll
;         for (int i = 0; i < 16; ++i) v[i] = *(const f32x4*)(W + (size_t)(k0 + 4 * i + lk) * N + n0 + ln);
; #pragma unroll
;         for (int i = 0; i < 16; ++i) { const int kk = 4 * i + lk; const float g = gk ? gk[k0 + kk] : 1.0f; LAS float* d = scr + kk * 65 + ln;
;             d[0] = v[i][0] * g; d[1] = v[i][1] * g; d[2] = v[i][2] * g; d[3] = v[i][3] * g; }
;     }
;     ...
; #pragma unroll
;     for (int hh = 0; hh < 2; ++hh) {
;         f32x4 v[8];
; #pragma unroll
;         for (int i = 0; i < 8; ++i) v[i] = *(const f32x4*)(W + (size_t)(k0 + 32 * hh + 4 * i + lk) * N + n0 + ln);
; #pragma unroll
;         for (int i = 0; i < 8; ++i) { const int kk = 32 * hh + 4 * i + lk; const float g = gk ? gk[k0 + kk] : 1.0f; LAS float* d = scr + kk * 65 + ln;
;             d[0] = v[i][0] * g; d[1] = v[i][1] * g; d[2] = v[i][2] * g; d[3] = v[i][3] * g; }
;     }
; __device__ __forceinline__ void cvt_item(const CvtCtx& c, int batch, int wi, LAS float* scr, int wave, int lane) {
;     ...
;     if (wi < CVT_OUT) { cvt_tile64<false>(c.w_out + (size_t)l * DM * DM, DM, DM, c.WoutT + (size_t)l * DM * DM, DM, nullptr, scr, 8 * wi + wave, lane); return; } wi -= CVT_OUT;
;     if (wi < CVT_UP) { cvt_tile64<false>(c.w_up + (size_t)l * DM * DFF, DM, DFF, c.WupT + (size_t)l * DFF * DM, DM, c.g_mlp + l * DM, scr, 8 * wi + wave, lane); return; } wi -= CVT_UP;
.LBB0_216:
	s_cmpk_gt_i32 s12, 0x1ff
	s_mov_b64 s[0:1], -1
	s_cbranch_scc0 .LBB0_236
	s_add_i32 s0, s5, 0xfffff000
	s_ashr_i32 s1, s0, 31
	s_lshr_b32 s1, s1, 24
	s_add_i32 s0, s0, s1
	s_ashr_i32 s0, s0, 8
	s_lshl_b32 s14, s0, 6
	s_lshl_b32 s13, s0, 14
	s_sub_i32 s0, s4, s13
	v_or_b32_e32 v44, s14, v16
	s_add_i32 s0, s0, 0xfffc0000
	v_or_b32_e32 v2, 4, v44
	s_ashr_i32 s1, s0, 31
	v_ashrrev_i32_e32 v45, 31, v44
	v_ashrrev_i32_e32 v3, 31, v2
	v_lshl_add_u64 v[42:43], s[0:1], 2, v[34:35]
	v_lshlrev_b64 v[0:1], 16, v[44:45]
	v_lshlrev_b64 v[2:3], 16, v[2:3]
	v_lshl_add_u64 v[0:1], v[42:43], 0, v[0:1]
	v_lshl_add_u64 v[2:3], v[42:43], 0, v[2:3]
	global_load_dwordx4 v[30:33], v[0:1], off
	global_load_dwordx4 v[26:29], v[2:3], off
	v_or_b32_e32 v0, 8, v44
	v_or_b32_e32 v2, 12, v44
	v_ashrrev_i32_e32 v1, 31, v0
	v_ashrrev_i32_e32 v3, 31, v2
	v_lshlrev_b64 v[0:1], 16, v[0:1]
	v_lshlrev_b64 v[2:3], 16, v[2:3]
	v_lshl_add_u64 v[0:1], v[42:43], 0, v[0:1]
	v_lshl_add_u64 v[2:3], v[42:43], 0, v[2:3]
	global_load_dwordx4 v[22:25], v[0:1], off
	global_load_dwordx4 v[18:21], v[2:3], off
	v_or_b32_e32 v0, 16, v44
	v_or_b32_e32 v2, 20, v44
	v_ashrrev_i32_e32 v1, 31, v0
	v_ashrrev_i32_e32 v3, 31, v2
	v_lshlrev_b64 v[0:1], 16, v[0:1]
	v_lshlrev_b64 v[2:3], 16, v[2:3]
	v_lshl_add_u64 v[0:1], v[42:43], 0, v[0:1]
	v_lshl_add_u64 v[2:3], v[42:43], 0, v[2:3]
	global_load_dwordx4 v[12:15], v[0:1], off
	global_load_dwordx4 v[8:11], v[2:3], off
	v_or_b32_e32 v0, 24, v44
	v_or_b32_e32 v2, 28, v44
	v_ashrrev_i32_e32 v1, 31, v0
	v_ashrrev_i32_e32 v3, 31, v2
	v_lshlrev_b64 v[0:1], 16, v[0:1]
	v_lshlrev_b64 v[2:3], 16, v[2:3]
	v_lshl_add_u64 v[0:1], v[42:43], 0, v[0:1]
	v_lshl_add_u64 v[2:3], v[42:43], 0, v[2:3]
	global_load_dwordx4 v[4:7], v[0:1], off
	s_nop 0
	global_load_dwordx4 v[0:3], v[2:3], off
	v_cndmask_b32_e64 v48, 0, 1, s[10:11]
	v_mov_b32_e32 v46, 1.0
	v_cmp_ne_u32_e64 s[6:7], 1, v48
	s_andn2_b64 vcc, exec, s[10:11]
	v_mov_b32_e32 v48, 1.0
	s_cbranch_vccnz .LBB0_219
	v_lshl_add_u64 v[52:53], v[44:45], 2, s[8:9]
	global_load_dword v110, v[52:53], off offset:16
	global_load_dword v124, v[52:53], off offset:32
	global_load_dword v125, v[52:53], off offset:48
	global_load_dword v126, v[52:53], off offset:64
	global_load_dword v127, v[52:53], off offset:80
	global_load_dword v178, v[52:53], off offset:96
	global_load_dword v179, v[52:53], off offset:112
	global_load_dword v180, v[52:53], off offset:128
	global_load_dword v181, v[52:53], off offset:144
	global_load_dword v182, v[52:53], off offset:160
	global_load_dword v183, v[52:53], off offset:176
	global_load_dword v184, v[52:53], off offset:192
	global_load_dword v185, v[52:53], off offset:208
	global_load_dword v186, v[52:53], off offset:224
	global_load_dword v187, v[52:53], off offset:240
	global_load_dword v48, v[52:53], off
	s_waitcnt vmcnt(0)
	s_ashr_i32 s15, s14, 31
	v_lshl_add_u64 v[52:53], s[14:15], 0, v[16:17]
	v_lshl_add_u64 v[52:53], v[52:53], 2, s[8:9]
	s_waitcnt vmcnt(0)
	v_pk_mul_f32 v[30:31], v[30:31], v[48:49] op_sel_hi:[1,0]
	v_pk_mul_f32 v[32:33], v[32:33], v[48:49] op_sel_hi:[1,0]
	v_mov_b32_e32 v48, v110
.LBB0_219:
	v_add_u32_e32 v45, v47, v49
	s_waitcnt vmcnt(7)
	ds_write2_b32 v45, v30, v31 offset1:1
	ds_write2_b32 v45, v32, v33 offset0:2 offset1:3
	s_waitcnt vmcnt(0)
	v_pk_mul_f32 v[26:27], v[26:27], v[48:49] op_sel_hi:[1,0]
	v_add_u32_e32 v30, 0x410, v45
	ds_write2_b32 v30, v26, v27 offset1:1
	v_pk_mul_f32 v[26:27], v[28:29], v[48:49] op_sel_hi:[1,0]
	v_add_u32_e32 v28, 0x418, v45
	s_and_b64 vcc, exec, s[6:7]
	ds_write2_b32 v28, v26, v27 offset1:1
	s_cbranch_vccnz .LBB0_221
	s_ashr_i32 s15, s14, 31
	v_lshl_add_u64 v[26:27], s[14:15], 0, v[16:17]
	v_lshl_add_u64 v[26:27], v[26:27], 2, s[8:9]
	v_mov_b32_e32 v28, v124
	v_mov_b32_e32 v46, v125
	s_waitcnt vmcnt(1)
	v_pk_mul_f32 v[22:23], v[22:23], v[28:29] op_sel_hi:[1,0]
	v_pk_mul_f32 v[24:25], v[24:25], v[28:29] op_sel_hi:[1,0]
.LBB0_221:
	v_add_u32_e32 v26, 0x820, v45
	ds_write2_b32 v26, v22, v23 offset1:1
	v_add_u32_e32 v22, 0x828, v45
	ds_write2_b32 v22, v24, v25 offset1:1
	s_waitcnt vmcnt(0)
	v_pk_mul_f32 v[18:19], v[18:19], v[46:47] op_sel_hi:[1,0]
	v_add_u32_e32 v22, 0xc30, v45
	ds_write2_b32 v22, v18, v19 offset1:1
	v_pk_mul_f32 v[18:19], v[20:21], v[46:47] op_sel_hi:[1,0]
	v_add_u32_e32 v20, 0xc38, v45
	ds_write2_b32 v20, v18, v19 offset1:1
	v_mov_b32_e32 v18, 1.0
	s_and_b64 vcc, exec, s[6:7]
	v_mov_b32_e32 v20, 1.0
	s_cbranch_vccnz .LBB0_223
	s_ashr_i32 s15, s14, 31
	v_lshl_add_u64 v[20:21], s[14:15], 0, v[16:17]
	v_lshl_add_u64 v[20:21], v[20:21], 2, s[8:9]
	v_mov_b32_e32 v22, v126
	s_waitcnt vmcnt(0)
	v_pk_mul_f32 v[12:13], v[12:13], v[22:23] op_sel_hi:[1,0]
	v_mov_b32_e32 v20, v127
	v_pk_mul_f32 v[14:15], v[14:15], v[22:23] op_sel_hi:[1,0]
; #define LAS __attribute__((address_space(3)))
; template <bool PERMUTE, bool BLOCKED = false>
; __device__ __forceinline__ void cvt_tile64(const float* W, int K, int N, bf16* WT, int ldo, const float* gk, LAS float* scr, int tile, int lane) {
;     ...
; #pragma unroll
;     for (int hh = 0; hh < 2; ++hh) {
;         f32x4 v[8];
; #pragma unroll
;         for (int i = 0; i < 8; ++i) v[i] = *(const f32x4*)(W + (size_t)(k0 + 32 * hh + 4 * i + lk) * N + n0 + ln);
; #pragma unroll
;         for (int i = 0; i < 8; ++i) { const int kk = 32 * hh + 4 * i + lk; const float g = gk ? gk[k0 + kk] : 1.0f; LAS float* d = scr + kk * 65 + ln;
;             d[0] = v[i][0] * g; d[1] = v[i][1] * g; d[2] = v[i][2] * g; d[3] = v[i][3] * g; }
;     }
.LBB0_223:
	v_add_u32_e32 v19, 0x1040, v45
	ds_write2_b32 v19, v12, v13 offset1:1
	v_add_u32_e32 v12, 0x1048, v45
	ds_write2_b32 v12, v14, v15 offset1:1
	s_waitcnt vmcnt(0)
	v_pk_mul_f32 v[8:9], v[8:9], v[20:21] op_sel_hi:[1,0]
	v_add_u32_e32 v12, 0x1450, v45
	ds_write2_b32 v12, v8, v9 offset1:1
	v_pk_mul_f32 v[8:9], v[10:11], v[20:21] op_sel_hi:[1,0]
	v_add_u32_e32 v10, 0x1458, v45
	s_and_b64 vcc, exec, s[6:7]
	ds_write2_b32 v10, v8, v9 offset1:1
	s_cbranch_vccnz .LBB0_225
	s_ashr_i32 s15, s14, 31
	v_lshl_add_u64 v[8:9], s[14:15], 0, v[16:17]
	v_lshl_add_u64 v[8:9], v[8:9], 2, s[8:9]
	v_mov_b32_e32 v10, v178
	v_mov_b32_e32 v18, v179
	s_waitcnt vmcnt(1)
	v_pk_mul_f32 v[4:5], v[4:5], v[10:11] op_sel_hi:[1,0]
	v_pk_mul_f32 v[6:7], v[6:7], v[10:11] op_sel_hi:[1,0]
.LBB0_225:
	v_add_u32_e32 v8, 0x1860, v45
	ds_write2_b32 v8, v4, v5 offset1:1
	v_add_u32_e32 v4, 0x1868, v45
	ds_write2_b32 v4, v6, v7 offset1:1
	s_waitcnt vmcnt(0)
	v_pk_mul_f32 v[0:1], v[0:1], v[18:19] op_sel_hi:[1,0]
	v_add_u32_e32 v4, 0x1c70, v45
	ds_write2_b32 v4, v0, v1 offset1:1
	v_pk_mul_f32 v[0:1], v[2:3], v[18:19] op_sel_hi:[1,0]
	v_add_u32_e32 v2, 0x1c78, v45
	ds_write2_b32 v2, v0, v1 offset1:1
	v_or_b32_e32 v0, 32, v44
	v_or_b32_e32 v4, 60, v44
	v_ashrrev_i32_e32 v1, 31, v0
	v_ashrrev_i32_e32 v5, 31, v4
	v_lshlrev_b64 v[0:1], 16, v[0:1]
	v_lshlrev_b64 v[4:5], 16, v[4:5]
	v_lshl_add_u64 v[0:1], v[42:43], 0, v[0:1]
	v_lshl_add_u64 v[4:5], v[42:43], 0, v[4:5]
	global_load_dwordx4 v[26:29], v[0:1], off
	s_and_b64 vcc, exec, s[6:7]
	global_load_dwordx4 v[4:7], v[4:5], off
	v_or_b32_e32 v0, 36, v44
	v_ashrrev_i32_e32 v1, 31, v0
	v_lshlrev_b64 v[0:1], 16, v[0:1]
	v_lshl_add_u64 v[0:1], v[42:43], 0, v[0:1]
	global_load_dwordx4 v[30:33], v[0:1], off
	v_or_b32_e32 v0, 40, v44
	v_ashrrev_i32_e32 v1, 31, v0
	v_lshlrev_b64 v[0:1], 16, v[0:1]
	v_lshl_add_u64 v[0:1], v[42:43], 0, v[0:1]
	global_load_dwordx4 v[18:21], v[0:1], off
	v_or_b32_e32 v0, 44, v44
	v_ashrrev_i32_e32 v1, 31, v0
	v_lshlrev_b64 v[0:1], 16, v[0:1]
	v_lshl_add_u64 v[0:1], v[42:43], 0, v[0:1]
	global_load_dwordx4 v[22:25], v[0:1], off
	v_or_b32_e32 v0, 48, v44
	v_ashrrev_i32_e32 v1, 31, v0
	v_lshlrev_b64 v[0:1], 16, v[0:1]
	v_lshl_add_u64 v[0:1], v[42:43], 0, v[0:1]
	global_load_dwordx4 v[8:11], v[0:1], off
	v_or_b32_e32 v0, 52, v44
	v_ashrrev_i32_e32 v1, 31, v0
	v_lshlrev_b64 v[0:1], 16, v[0:1]
	v_lshl_add_u64 v[0:1], v[42:43], 0, v[0:1]
	global_load_dwordx4 v[12:15], v[0:1], off
	v_or_b32_e32 v0, 56, v44
	v_ashrrev_i32_e32 v1, 31, v0
	v_lshlrev_b64 v[0:1], 16, v[0:1]
	v_lshl_add_u64 v[0:1], v[42:43], 0, v[0:1]
	global_load_dwordx4 v[0:3], v[0:1], off
	v_mov_b32_e32 v42, 1.0
	v_mov_b32_e32 v44, 1.0
	s_cbranch_vccnz .LBB0_227
	s_ashr_i32 s15, s14, 31
	v_lshl_add_u64 v[52:53], s[14:15], 0, v[16:17]
	v_lshl_add_u64 v[52:53], v[52:53], 2, s[8:9]
	v_mov_b32_e32 v44, v180
	s_waitcnt vmcnt(0)
	v_pk_mul_f32 v[26:27], v[26:27], v[44:45] op_sel_hi:[1,0]
	v_pk_mul_f32 v[28:29], v[28:29], v[44:45] op_sel_hi:[1,0]
	v_mov_b32_e32 v44, v181
.LBB0_227:
	v_add_u32_e32 v43, 0x2080, v45
	s_waitcnt vmcnt(7)
	ds_write2_b32 v43, v26, v27 offset1:1
	v_add_u32_e32 v26, 0x2088, v45
	ds_write2_b32 v26, v28, v29 offset1:1
	s_waitcnt vmcnt(0)
	v_pk_mul_f32 v[26:27], v[30:31], v[44:45] op_sel_hi:[1,0]
	v_add_u32_e32 v28, 0x2490, v45
	ds_write2_b32 v28, v26, v27 offset1:1
	v_pk_mul_f32 v[26:27], v[32:33], v[44:45] op_sel_hi:[1,0]
	v_add_u32_e32 v28, 0x2498, v45
	s_and_b64 vcc, exec, s[6:7]
	ds_write2_b32 v28, v26, v27 offset1:1
	s_cbranch_vccnz .LBB0_229
	s_ashr_i32 s15, s14, 31
	v_lshl_add_u64 v[26:27], s[14:15], 0, v[16:17]
	v_lshl_add_u64 v[26:27], v[26:27], 2, s[8:9]
	v_mov_b32_e32 v28, v182
	v_mov_b32_e32 v42, v183
	s_waitcnt vmcnt(1)
	v_pk_mul_f32 v[18:19], v[18:19], v[28:29] op_sel_hi:[1,0]
	v_pk_mul_f32 v[20:21], v[20:21], v[28:29] op_sel_hi:[1,0]
.LBB0_229:
	v_add_u32_e32 v26, 0x28a0, v45
	ds_write2_b32 v26, v18, v19 offset1:1
	v_add_u32_e32 v18, 0x28a8, v45
	ds_write2_b32 v18, v20, v21 offset1:1
	s_waitcnt vmcnt(0)
	v_pk_mul_f32 v[18:19], v[22:23], v[42:43] op_sel_hi:[1,0]
	v_add_u32_e32 v20, 0x2cb0, v45
	ds_write2_b32 v20, v18, v19 offset1:1
	v_pk_mul_f32 v[18:19], v[24:25], v[42:43] op_sel_hi:[1,0]
	v_add_u32_e32 v20, 0x2cb8, v45
	s_and_b64 vcc, exec, s[6:7]
	ds_write2_b32 v20, v18, v19 offset1:1
	s_cbranch_vccnz .LBB0_231
	s_ashr_i32 s15, s14, 31
	v_lshl_add_u64 v[18:19], s[14:15], 0, v[16:17]
	v_lshl_add_u64 v[18:19], v[18:19], 2, s[8:9]
	v_mov_b32_e32 v20, v184
	s_waitcnt vmcnt(0)
	v_pk_mul_f32 v[8:9], v[8:9], v[20:21] op_sel_hi:[1,0]
	v_mov_b32_e32 v18, v185
	v_pk_mul_f32 v[10:11], v[10:11], v[20:21] op_sel_hi:[1,0]
	s_branch .LBB0_232

; #define LAS __attribute__((address_space(3)))
; template <bool PERMUTE, bool BLOCKED = false>
; __device__ __forceinline__ void cvt_tile64(const float* W, int K, int N, bf16* WT, int ldo, const float* gk, LAS float* scr, int tile, int lane) {
;     ...
;         for (int i = 0; i < 8; ++i) { const int kk = 32 * hh + 4 * i + lk; const float g = gk ? gk[k0 + kk] : 1.0f; LAS float* d = scr + kk * 65 + ln;
;             d[0] = v[i][0] * g; d[1] = v[i][1] * g; d[2] = v[i][2] * g; d[3] = v[i][3] * g; }
;     }
.LBB0_232:
	v_add_u32_e32 v19, 0x30c0, v45
	ds_write2_b32 v19, v8, v9 offset1:1
	v_add_u32_e32 v8, 0x30c8, v45
	ds_write2_b32 v8, v10, v11 offset1:1
	s_waitcnt vmcnt(0)
	v_pk_mul_f32 v[8:9], v[12:13], v[18:19] op_sel_hi:[1,0]
	v_add_u32_e32 v10, 0x34d0, v45
	ds_write2_b32 v10, v8, v9 offset1:1
	v_pk_mul_f32 v[8:9], v[14:15], v[18:19] op_sel_hi:[1,0]
	v_add_u32_e32 v10, 0x34d8, v45
	s_and_b64 vcc, exec, s[10:11]
	ds_write2_b32 v10, v8, v9 offset1:1
	s_cbranch_vccz .LBB0_238
	s_ashr_i32 s15, s14, 31
	v_lshl_add_u64 v[8:9], s[14:15], 0, v[16:17]
	v_lshl_add_u64 v[8:9], v[8:9], 2, s[8:9]
	v_mov_b32_e32 v10, v186
	s_nop 0
	v_mov_b32_e32 v8, v187
	s_waitcnt vmcnt(1)
	v_pk_mul_f32 v[0:1], v[0:1], v[10:11] op_sel_hi:[1,0]
	v_pk_mul_f32 v[2:3], v[2:3], v[10:11] op_sel_hi:[1,0]
	s_cbranch_execnz .LBB0_235

; #define LAS __attribute__((address_space(3)))
; template <bool PERMUTE, bool BLOCKED = false>
; __device__ __forceinline__ void cvt_tile64(const float* W, int K, int N, bf16* WT, int ldo, const float* gk, LAS float* scr, int tile, int lane) {
;     const int nblk = N >> 6, kb = tile / nblk, nb = tile - kb * nblk, k0 = 64 * kb, n0 = 64 * nb;
;     const int lk = lane >> 4, ln = (lane & 15) * 4;
;     ...
;     {
;         f32x4 v[16];
; #pragma unroll
;         for (int i = 0; i < 16; ++i) v[i] = *(const f32x4*)(W + (size_t)(k0 + 4 * i + lk) * N + n0 + ln);
; #pragma unroll
;         for (int i = 0; i < 16; ++i) { const int kk = 4 * i + lk; const float g = gk ? gk[k0 + kk] : 1.0f; LAS float* d = scr + kk * 65 + ln;
;             d[0] = v[i][0] * g; d[1] = v[i][1] * g; d[2] = v[i][2] * g; d[3] = v[i][3] * g; }
;     }
;     ...
; #pragma unroll
;     for (int hh = 0; hh < 2; ++hh) {
;         f32x4 v[8];
; #pragma unroll
;         for (int i = 0; i < 8; ++i) v[i] = *(const f32x4*)(W + (size_t)(k0 + 32 * hh + 4 * i + lk) * N + n0 + ln);
; #pragma unroll
;         for (int i = 0; i < 8; ++i) { const int kk = 32 * hh + 4 * i + lk; const float g = gk ? gk[k0 + kk] : 1.0f; LAS float* d = scr + kk * 65 + ln;
;             d[0] = v[i][0] * g; d[1] = v[i][1] * g; d[2] = v[i][2] * g; d[3] = v[i][3] * g; }
;     }
; __device__ __forceinline__ void cvt_item(const CvtCtx& c, int batch, int wi, LAS float* scr, int wave, int lane) {
;     ...
;     if (wi < CVT_OUT) { cvt_tile64<false>(c.w_out + (size_t)l * DM * DM, DM, DM, c.WoutT + (size_t)l * DM * DM, DM, nullptr, scr, 8 * wi + wave, lane); return; } wi -= CVT_OUT;
;     if (wi < CVT_UP) { cvt_tile64<false>(c.w_up + (size_t)l * DM * DFF, DM, DFF, c.WupT + (size_t)l * DFF * DM, DM, c.g_mlp + l * DM, scr, 8 * wi + wave, lane); return; } wi -= CVT_UP;
.LBB0_524:
	s_andn2_b64 vcc, exec, s[0:1]
	s_cbranch_vccnz .LBB0_544
	s_add_i32 s0, s5, 0xfffff000
	s_ashr_i32 s1, s0, 31
	s_lshr_b32 s1, s1, 24
	s_add_i32 s0, s0, s1
	s_ashr_i32 s0, s0, 8
	s_lshl_b32 s20, s0, 6
	s_lshl_b32 s16, s0, 14
	s_add_i32 s0, s4, s12
	s_sub_i32 s0, s0, s16
	v_or_b32_e32 v48, s20, v16
	s_add_i32 s0, s0, 0x74000
	v_or_b32_e32 v2, 4, v48
	s_ashr_i32 s1, s0, 31
	v_ashrrev_i32_e32 v49, 31, v48
	v_ashrrev_i32_e32 v3, 31, v2
	v_lshl_add_u64 v[46:47], s[0:1], 2, v[38:39]
	v_lshlrev_b64 v[0:1], 16, v[48:49]
	v_lshlrev_b64 v[2:3], 16, v[2:3]
	v_lshl_add_u64 v[0:1], v[46:47], 0, v[0:1]
	v_lshl_add_u64 v[2:3], v[46:47], 0, v[2:3]
	global_load_dwordx4 v[30:33], v[0:1], off
	global_load_dwordx4 v[26:29], v[2:3], off
	v_or_b32_e32 v0, 8, v48
	v_or_b32_e32 v2, 12, v48
	v_ashrrev_i32_e32 v1, 31, v0
	v_ashrrev_i32_e32 v3, 31, v2
	v_lshlrev_b64 v[0:1], 16, v[0:1]
	v_lshlrev_b64 v[2:3], 16, v[2:3]
	v_lshl_add_u64 v[0:1], v[46:47], 0, v[0:1]
	v_lshl_add_u64 v[2:3], v[46:47], 0, v[2:3]
	global_load_dwordx4 v[22:25], v[0:1], off
	global_load_dwordx4 v[18:21], v[2:3], off
	v_or_b32_e32 v0, 16, v48
	v_or_b32_e32 v2, 20, v48
	v_ashrrev_i32_e32 v1, 31, v0
	v_ashrrev_i32_e32 v3, 31, v2
	v_lshlrev_b64 v[0:1], 16, v[0:1]
	v_lshlrev_b64 v[2:3], 16, v[2:3]
	v_lshl_add_u64 v[0:1], v[46:47], 0, v[0:1]
	v_lshl_add_u64 v[2:3], v[46:47], 0, v[2:3]
	global_load_dwordx4 v[12:15], v[0:1], off
	global_load_dwordx4 v[8:11], v[2:3], off
	v_or_b32_e32 v0, 24, v48
	v_or_b32_e32 v2, 28, v48
	v_ashrrev_i32_e32 v1, 31, v0
	v_ashrrev_i32_e32 v3, 31, v2
	v_lshlrev_b64 v[0:1], 16, v[0:1]
	v_lshlrev_b64 v[2:3], 16, v[2:3]
	v_lshl_add_u64 v[0:1], v[46:47], 0, v[0:1]
	v_lshl_add_u64 v[2:3], v[46:47], 0, v[2:3]
	global_load_dwordx4 v[4:7], v[0:1], off
	s_nop 0
	global_load_dwordx4 v[0:3], v[2:3], off
	v_cndmask_b32_e64 v52, 0, 1, s[14:15]
	v_mov_b32_e32 v50, 1.0
	v_cmp_ne_u32_e64 s[6:7], 1, v52
	s_andn2_b64 vcc, exec, s[14:15]
	v_mov_b32_e32 v52, 1.0
	s_cbranch_vccnz .LBB0_527
	v_lshl_add_u64 v[64:65], v[48:49], 2, s[10:11]
	global_load_dword v110, v[64:65], off offset:16
	global_load_dword v124, v[64:65], off offset:32
	global_load_dword v125, v[64:65], off offset:48
	global_load_dword v126, v[64:65], off offset:64
	global_load_dword v127, v[64:65], off offset:80
	global_load_dword v178, v[64:65], off offset:96
	global_load_dword v179, v[64:65], off offset:112
	global_load_dword v180, v[64:65], off offset:128
	global_load_dword v181, v[64:65], off offset:144
	global_load_dword v182, v[64:65], off offset:160
	global_load_dword v183, v[64:65], off offset:176
	global_load_dword v184, v[64:65], off offset:192
	global_load_dword v185, v[64:65], off offset:208
	global_load_dword v186, v[64:65], off offset:224
	global_load_dword v187, v[64:65], off offset:240
	global_load_dword v52, v[64:65], off
	s_waitcnt vmcnt(0)
	s_ashr_i32 s21, s20, 31
	v_lshl_add_u64 v[64:65], s[20:21], 0, v[16:17]
	v_lshl_add_u64 v[64:65], v[64:65], 2, s[10:11]
	s_waitcnt vmcnt(0)
	v_pk_mul_f32 v[30:31], v[30:31], v[52:53] op_sel_hi:[1,0]
	v_pk_mul_f32 v[32:33], v[32:33], v[52:53] op_sel_hi:[1,0]
	v_mov_b32_e32 v52, v110
.LBB0_527:
	v_add_u32_e32 v49, v51, v53
	s_waitcnt vmcnt(7)
	ds_write2_b32 v49, v30, v31 offset1:1
	ds_write2_b32 v49, v32, v33 offset0:2 offset1:3
	s_waitcnt vmcnt(0)
	v_pk_mul_f32 v[26:27], v[26:27], v[52:53] op_sel_hi:[1,0]
	v_add_u32_e32 v30, 0x410, v49
	ds_write2_b32 v30, v26, v27 offset1:1
	v_pk_mul_f32 v[26:27], v[28:29], v[52:53] op_sel_hi:[1,0]
	v_add_u32_e32 v28, 0x418, v49
	s_and_b64 vcc, exec, s[6:7]
	ds_write2_b32 v28, v26, v27 offset1:1
	s_cbranch_vccnz .LBB0_529
	s_ashr_i32 s21, s20, 31
	v_lshl_add_u64 v[26:27], s[20:21], 0, v[16:17]
	v_lshl_add_u64 v[26:27], v[26:27], 2, s[10:11]
	v_mov_b32_e32 v28, v124
	v_mov_b32_e32 v50, v125
	s_waitcnt vmcnt(1)
	v_pk_mul_f32 v[22:23], v[22:23], v[28:29] op_sel_hi:[1,0]
	v_pk_mul_f32 v[24:25], v[24:25], v[28:29] op_sel_hi:[1,0]
.LBB0_529:
	v_add_u32_e32 v26, 0x820, v49
	ds_write2_b32 v26, v22, v23 offset1:1
	v_add_u32_e32 v22, 0x828, v49
	ds_write2_b32 v22, v24, v25 offset1:1
	s_waitcnt vmcnt(0)
	v_pk_mul_f32 v[18:19], v[18:19], v[50:51] op_sel_hi:[1,0]
	v_add_u32_e32 v22, 0xc30, v49
	ds_write2_b32 v22, v18, v19 offset1:1
	v_pk_mul_f32 v[18:19], v[20:21], v[50:51] op_sel_hi:[1,0]
	v_add_u32_e32 v20, 0xc38, v49
	ds_write2_b32 v20, v18, v19 offset1:1
	v_mov_b32_e32 v18, 1.0
	s_and_b64 vcc, exec, s[6:7]
	v_mov_b32_e32 v20, 1.0
	s_cbranch_vccnz .LBB0_531
	s_ashr_i32 s21, s20, 31
	v_lshl_add_u64 v[20:21], s[20:21], 0, v[16:17]
	v_lshl_add_u64 v[20:21], v[20:21], 2, s[10:11]
	v_mov_b32_e32 v22, v126
	s_waitcnt vmcnt(0)
	v_pk_mul_f32 v[12:13], v[12:13], v[22:23] op_sel_hi:[1,0]
	v_mov_b32_e32 v20, v127
	v_pk_mul_f32 v[14:15], v[14:15], v[22:23] op_sel_hi:[1,0]
; #define LAS __attribute__((address_space(3)))
; template <bool PERMUTE, bool BLOCKED = false>
; __device__ __forceinline__ void cvt_tile64(const float* W, int K, int N, bf16* WT, int ldo, const float* gk, LAS float* scr, int tile, int lane) {
;     ...
; #pragma unroll
;     for (int hh = 0; hh < 2; ++hh) {
;         f32x4 v[8];
; #pragma unroll
;         for (int i = 0; i < 8; ++i) v[i] = *(const f32x4*)(W + (size_t)(k0 + 32 * hh + 4 * i + lk) * N + n0 + ln);
; #pragma unroll
;         for (int i = 0; i < 8; ++i) { const int kk = 32 * hh + 4 * i + lk; const float g = gk ? gk[k0 + kk] : 1.0f; LAS float* d = scr + kk * 65 + ln;
;             d[0] = v[i][0] * g; d[1] = v[i][1] * g; d[2] = v[i][2] * g; d[3] = v[i][3] * g; }
;     }
.LBB0_531:
	v_add_u32_e32 v19, 0x1040, v49
	ds_write2_b32 v19, v12, v13 offset1:1
	v_add_u32_e32 v12, 0x1048, v49
	ds_write2_b32 v12, v14, v15 offset1:1
	s_waitcnt vmcnt(0)
	v_pk_mul_f32 v[8:9], v[8:9], v[20:21] op_sel_hi:[1,0]
	v_add_u32_e32 v12, 0x1450, v49
	ds_write2_b32 v12, v8, v9 offset1:1
	v_pk_mul_f32 v[8:9], v[10:11], v[20:21] op_sel_hi:[1,0]
	v_add_u32_e32 v10, 0x1458, v49
	s_and_b64 vcc, exec, s[6:7]
	ds_write2_b32 v10, v8, v9 offset1:1
	s_cbranch_vccnz .LBB0_533
	s_ashr_i32 s21, s20, 31
	v_lshl_add_u64 v[8:9], s[20:21], 0, v[16:17]
	v_lshl_add_u64 v[8:9], v[8:9], 2, s[10:11]
	v_mov_b32_e32 v10, v178
	v_mov_b32_e32 v18, v179
	s_waitcnt vmcnt(1)
	v_pk_mul_f32 v[4:5], v[4:5], v[10:11] op_sel_hi:[1,0]
	v_pk_mul_f32 v[6:7], v[6:7], v[10:11] op_sel_hi:[1,0]
.LBB0_533:
	v_add_u32_e32 v8, 0x1860, v49
	ds_write2_b32 v8, v4, v5 offset1:1
	v_add_u32_e32 v4, 0x1868, v49
	ds_write2_b32 v4, v6, v7 offset1:1
	s_waitcnt vmcnt(0)
	v_pk_mul_f32 v[0:1], v[0:1], v[18:19] op_sel_hi:[1,0]
	v_add_u32_e32 v4, 0x1c70, v49
	ds_write2_b32 v4, v0, v1 offset1:1
	v_pk_mul_f32 v[0:1], v[2:3], v[18:19] op_sel_hi:[1,0]
	v_add_u32_e32 v2, 0x1c78, v49
	ds_write2_b32 v2, v0, v1 offset1:1
	v_or_b32_e32 v0, 32, v48
	v_or_b32_e32 v4, 60, v48
	v_ashrrev_i32_e32 v1, 31, v0
	v_ashrrev_i32_e32 v5, 31, v4
	v_lshlrev_b64 v[0:1], 16, v[0:1]
	v_lshlrev_b64 v[4:5], 16, v[4:5]
	v_lshl_add_u64 v[0:1], v[46:47], 0, v[0:1]
	v_lshl_add_u64 v[4:5], v[46:47], 0, v[4:5]
	global_load_dwordx4 v[26:29], v[0:1], off
	s_and_b64 vcc, exec, s[6:7]
	global_load_dwordx4 v[4:7], v[4:5], off
	v_or_b32_e32 v0, 36, v48
	v_ashrrev_i32_e32 v1, 31, v0
	v_lshlrev_b64 v[0:1], 16, v[0:1]
	v_lshl_add_u64 v[0:1], v[46:47], 0, v[0:1]
	global_load_dwordx4 v[30:33], v[0:1], off
	v_or_b32_e32 v0, 40, v48
	v_ashrrev_i32_e32 v1, 31, v0
	v_lshlrev_b64 v[0:1], 16, v[0:1]
	v_lshl_add_u64 v[0:1], v[46:47], 0, v[0:1]
	global_load_dwordx4 v[18:21], v[0:1], off
	v_or_b32_e32 v0, 44, v48
	v_ashrrev_i32_e32 v1, 31, v0
	v_lshlrev_b64 v[0:1], 16, v[0:1]
	v_lshl_add_u64 v[0:1], v[46:47], 0, v[0:1]
	global_load_dwordx4 v[22:25], v[0:1], off
	v_or_b32_e32 v0, 48, v48
	v_ashrrev_i32_e32 v1, 31, v0
	v_lshlrev_b64 v[0:1], 16, v[0:1]
	v_lshl_add_u64 v[0:1], v[46:47], 0, v[0:1]
	global_load_dwordx4 v[8:11], v[0:1], off
	v_or_b32_e32 v0, 52, v48
	v_ashrrev_i32_e32 v1, 31, v0
	v_lshlrev_b64 v[0:1], 16, v[0:1]
	v_lshl_add_u64 v[0:1], v[46:47], 0, v[0:1]
	global_load_dwordx4 v[12:15], v[0:1], off
	v_or_b32_e32 v0, 56, v48
	v_ashrrev_i32_e32 v1, 31, v0
	v_lshlrev_b64 v[0:1], 16, v[0:1]
	v_lshl_add_u64 v[0:1], v[46:47], 0, v[0:1]
	global_load_dwordx4 v[0:3], v[0:1], off
	v_mov_b32_e32 v46, 1.0
	v_mov_b32_e32 v48, 1.0
	s_cbranch_vccnz .LBB0_535
	s_ashr_i32 s21, s20, 31
	v_lshl_add_u64 v[64:65], s[20:21], 0, v[16:17]
	v_lshl_add_u64 v[64:65], v[64:65], 2, s[10:11]
	v_mov_b32_e32 v48, v180
	s_waitcnt vmcnt(0)
	v_pk_mul_f32 v[26:27], v[26:27], v[48:49] op_sel_hi:[1,0]
	v_pk_mul_f32 v[28:29], v[28:29], v[48:49] op_sel_hi:[1,0]
	v_mov_b32_e32 v48, v181
.LBB0_535:
	v_add_u32_e32 v47, 0x2080, v49
	s_waitcnt vmcnt(7)
	ds_write2_b32 v47, v26, v27 offset1:1
	v_add_u32_e32 v26, 0x2088, v49
	ds_write2_b32 v26, v28, v29 offset1:1
	s_waitcnt vmcnt(0)
	v_pk_mul_f32 v[26:27], v[30:31], v[48:49] op_sel_hi:[1,0]
	v_add_u32_e32 v28, 0x2490, v49
	ds_write2_b32 v28, v26, v27 offset1:1
	v_pk_mul_f32 v[26:27], v[32:33], v[48:49] op_sel_hi:[1,0]
	v_add_u32_e32 v28, 0x2498, v49
	s_and_b64 vcc, exec, s[6:7]
	ds_write2_b32 v28, v26, v27 offset1:1
	s_cbranch_vccnz .LBB0_537
	s_ashr_i32 s21, s20, 31
	v_lshl_add_u64 v[26:27], s[20:21], 0, v[16:17]
	v_lshl_add_u64 v[26:27], v[26:27], 2, s[10:11]
	v_mov_b32_e32 v28, v182
	v_mov_b32_e32 v46, v183
	s_waitcnt vmcnt(1)
	v_pk_mul_f32 v[18:19], v[18:19], v[28:29] op_sel_hi:[1,0]
	v_pk_mul_f32 v[20:21], v[20:21], v[28:29] op_sel_hi:[1,0]
.LBB0_537:
	v_add_u32_e32 v26, 0x28a0, v49
	ds_write2_b32 v26, v18, v19 offset1:1
	v_add_u32_e32 v18, 0x28a8, v49
	ds_write2_b32 v18, v20, v21 offset1:1
	s_waitcnt vmcnt(0)
	v_pk_mul_f32 v[18:19], v[22:23], v[46:47] op_sel_hi:[1,0]
	v_add_u32_e32 v20, 0x2cb0, v49
	ds_write2_b32 v20, v18, v19 offset1:1
	v_pk_mul_f32 v[18:19], v[24:25], v[46:47] op_sel_hi:[1,0]
	v_add_u32_e32 v20, 0x2cb8, v49
	s_and_b64 vcc, exec, s[6:7]
	ds_write2_b32 v20, v18, v19 offset1:1
	s_cbranch_vccnz .LBB0_539
	s_ashr_i32 s21, s20, 31
	v_lshl_add_u64 v[18:19], s[20:21], 0, v[16:17]
	v_lshl_add_u64 v[18:19], v[18:19], 2, s[10:11]
	v_mov_b32_e32 v20, v184
	s_waitcnt vmcnt(0)
	v_pk_mul_f32 v[8:9], v[8:9], v[20:21] op_sel_hi:[1,0]
	v_mov_b32_e32 v18, v185
	v_pk_mul_f32 v[10:11], v[10:11], v[20:21] op_sel_hi:[1,0]
	s_branch .LBB0_540

; #define LAS __attribute__((address_space(3)))
; template <bool PERMUTE, bool BLOCKED = false>
; __device__ __forceinline__ void cvt_tile64(const float* W, int K, int N, bf16* WT, int ldo, const float* gk, LAS float* scr, int tile, int lane) {
;     ...
;         for (int i = 0; i < 8; ++i) { const int kk = 32 * hh + 4 * i + lk; const float g = gk ? gk[k0 + kk] : 1.0f; LAS float* d = scr + kk * 65 + ln;
;             d[0] = v[i][0] * g; d[1] = v[i][1] * g; d[2] = v[i][2] * g; d[3] = v[i][3] * g; }
;     }
.LBB0_540:
	v_add_u32_e32 v19, 0x30c0, v49
	ds_write2_b32 v19, v8, v9 offset1:1
	v_add_u32_e32 v8, 0x30c8, v49
	ds_write2_b32 v8, v10, v11 offset1:1
	s_waitcnt vmcnt(0)
	v_pk_mul_f32 v[8:9], v[12:13], v[18:19] op_sel_hi:[1,0]
	v_add_u32_e32 v10, 0x34d0, v49
	ds_write2_b32 v10, v8, v9 offset1:1
	v_pk_mul_f32 v[8:9], v[14:15], v[18:19] op_sel_hi:[1,0]
	v_add_u32_e32 v10, 0x34d8, v49
	s_and_b64 vcc, exec, s[14:15]
	ds_write2_b32 v10, v8, v9 offset1:1
	s_cbranch_vccz .LBB0_547
	s_ashr_i32 s21, s20, 31
	v_lshl_add_u64 v[8:9], s[20:21], 0, v[16:17]
	v_lshl_add_u64 v[8:9], v[8:9], 2, s[10:11]
	v_mov_b32_e32 v10, v186
	s_nop 0
	v_mov_b32_e32 v8, v187
	s_waitcnt vmcnt(1)
	v_pk_mul_f32 v[0:1], v[0:1], v[10:11] op_sel_hi:[1,0]
	v_pk_mul_f32 v[2:3], v[2:3], v[10:11] op_sel_hi:[1,0]
	s_cbranch_execnz .LBB0_543

; #define LAS __attribute__((address_space(3)))
; template <bool PERMUTE, bool BLOCKED = false>
; __device__ __forceinline__ void cvt_tile64(const float* W, int K, int N, bf16* WT, int ldo, const float* gk, LAS float* scr, int tile, int lane) {
;     const int nblk = N >> 6, kb = tile / nblk, nb = tile - kb * nblk, k0 = 64 * kb, n0 = 64 * nb;
;     const int lk = lane >> 4, ln = (lane & 15) * 4;
;     ...
;     {
;         f32x4 v[16];
; #pragma unroll
;         for (int i = 0; i < 16; ++i) v[i] = *(const f32x4*)(W + (size_t)(k0 + 4 * i + lk) * N + n0 + ln);
; #pragma unroll
;         for (int i = 0; i < 16; ++i) { const int kk = 4 * i + lk; const float g = gk ? gk[k0 + kk] : 1.0f; LAS float* d = scr + kk * 65 + ln;
;             d[0] = v[i][0] * g; d[1] = v[i][1] * g; d[2] = v[i][2] * g; d[3] = v[i][3] * g; }
;     }
;     ...
; #pragma unroll
;     for (int hh = 0; hh < 2; ++hh) {
;         f32x4 v[8];
; #pragma unroll
;         for (int i = 0; i < 8; ++i) v[i] = *(const f32x4*)(W + (size_t)(k0 + 32 * hh + 4 * i + lk) * N + n0 + ln);
; #pragma unroll
;         for (int i = 0; i < 8; ++i) { const int kk = 32 * hh + 4 * i + lk; const float g = gk ? gk[k0 + kk] : 1.0f; LAS float* d = scr + kk * 65 + ln;
;             d[0] = v[i][0] * g; d[1] = v[i][1] * g; d[2] = v[i][2] * g; d[3] = v[i][3] * g; }
;     }
; __device__ __forceinline__ void cvt_item(const CvtCtx& c, int batch, int wi, LAS float* scr, int wave, int lane) {
;     ...
;     if (wi < CVT_OUT) { cvt_tile64<false>(c.w_out + (size_t)l * DM * DM, DM, DM, c.WoutT + (size_t)l * DM * DM, DM, nullptr, scr, 8 * wi + wave, lane); return; } wi -= CVT_OUT;
;     if (wi < CVT_UP) { cvt_tile64<false>(c.w_up + (size_t)l * DM * DFF, DM, DFF, c.WupT + (size_t)l * DFF * DM, DM, c.g_mlp + l * DM, scr, 8 * wi + wave, lane); return; } wi -= CVT_UP;
.LBB0_588:
	s_andn2_b64 vcc, exec, s[0:1]
	s_cbranch_vccnz .LBB0_608
	s_add_i32 s0, s13, 0xfffff000
	s_ashr_i32 s1, s0, 31
	s_lshr_b32 s1, s1, 24
	s_add_i32 s0, s0, s1
	s_ashr_i32 s0, s0, 8
	s_lshl_b32 s18, s0, 6
	s_lshl_b32 s20, s0, 14
	s_add_i32 s0, s12, s16
	s_sub_i32 s0, s0, s20
	v_or_b32_e32 v48, s18, v16
	s_add_i32 s0, s0, 0x74000
	v_or_b32_e32 v2, 4, v48
	s_ashr_i32 s1, s0, 31
	v_ashrrev_i32_e32 v49, 31, v48
	v_ashrrev_i32_e32 v3, 31, v2
	v_lshl_add_u64 v[46:47], s[0:1], 2, v[38:39]
	v_lshlrev_b64 v[0:1], 16, v[48:49]
	v_lshlrev_b64 v[2:3], 16, v[2:3]
	v_lshl_add_u64 v[0:1], v[46:47], 0, v[0:1]
	v_lshl_add_u64 v[2:3], v[46:47], 0, v[2:3]
	global_load_dwordx4 v[30:33], v[0:1], off
	global_load_dwordx4 v[26:29], v[2:3], off
	v_or_b32_e32 v0, 8, v48
	v_or_b32_e32 v2, 12, v48
	v_ashrrev_i32_e32 v1, 31, v0
	v_ashrrev_i32_e32 v3, 31, v2
	v_lshlrev_b64 v[0:1], 16, v[0:1]
	v_lshlrev_b64 v[2:3], 16, v[2:3]
	v_lshl_add_u64 v[0:1], v[46:47], 0, v[0:1]
	v_lshl_add_u64 v[2:3], v[46:47], 0, v[2:3]
	global_load_dwordx4 v[22:25], v[0:1], off
	global_load_dwordx4 v[18:21], v[2:3], off
	v_or_b32_e32 v0, 16, v48
	v_or_b32_e32 v2, 20, v48
	v_ashrrev_i32_e32 v1, 31, v0
	v_ashrrev_i32_e32 v3, 31, v2
	v_lshlrev_b64 v[0:1], 16, v[0:1]
	v_lshlrev_b64 v[2:3], 16, v[2:3]
	v_lshl_add_u64 v[0:1], v[46:47], 0, v[0:1]
	v_lshl_add_u64 v[2:3], v[46:47], 0, v[2:3]
	global_load_dwordx4 v[12:15], v[0:1], off
	global_load_dwordx4 v[8:11], v[2:3], off
	v_or_b32_e32 v0, 24, v48
	v_or_b32_e32 v2, 28, v48
	v_ashrrev_i32_e32 v1, 31, v0
	v_ashrrev_i32_e32 v3, 31, v2
	v_lshlrev_b64 v[0:1], 16, v[0:1]
	v_lshlrev_b64 v[2:3], 16, v[2:3]
	v_lshl_add_u64 v[0:1], v[46:47], 0, v[0:1]
	v_lshl_add_u64 v[2:3], v[46:47], 0, v[2:3]
	global_load_dwordx4 v[4:7], v[0:1], off
	s_nop 0
	global_load_dwordx4 v[0:3], v[2:3], off
	v_cndmask_b32_e64 v52, 0, 1, s[14:15]
	v_mov_b32_e32 v50, 1.0
	v_cmp_ne_u32_e64 s[4:5], 1, v52
	s_andn2_b64 vcc, exec, s[14:15]
	v_mov_b32_e32 v52, 1.0
	s_cbranch_vccnz .LBB0_591
	v_lshl_add_u64 v[64:65], v[48:49], 2, s[10:11]
	global_load_dword v110, v[64:65], off offset:16
	global_load_dword v124, v[64:65], off offset:32
	global_load_dword v125, v[64:65], off offset:48
	global_load_dword v126, v[64:65], off offset:64
	global_load_dword v127, v[64:65], off offset:80
	global_load_dword v178, v[64:65], off offset:96
	global_load_dword v179, v[64:65], off offset:112
	global_load_dword v180, v[64:65], off offset:128
	global_load_dword v181, v[64:65], off offset:144
	global_load_dword v182, v[64:65], off offset:160
	global_load_dword v183, v[64:65], off offset:176
	global_load_dword v184, v[64:65], off offset:192
	global_load_dword v185, v[64:65], off offset:208
	global_load_dword v186, v[64:65], off offset:224
	global_load_dword v187, v[64:65], off offset:240
	global_load_dword v52, v[64:65], off
	s_waitcnt vmcnt(0)
	s_ashr_i32 s19, s18, 31
	v_lshl_add_u64 v[64:65], s[18:19], 0, v[16:17]
	v_lshl_add_u64 v[64:65], v[64:65], 2, s[10:11]
	s_waitcnt vmcnt(0)
	v_pk_mul_f32 v[30:31], v[30:31], v[52:53] op_sel_hi:[1,0]
	v_pk_mul_f32 v[32:33], v[32:33], v[52:53] op_sel_hi:[1,0]
	v_mov_b32_e32 v52, v110
.LBB0_591:
	v_add_u32_e32 v49, v51, v53
	s_waitcnt vmcnt(7)
	ds_write2_b32 v49, v30, v31 offset1:1
	ds_write2_b32 v49, v32, v33 offset0:2 offset1:3
	s_waitcnt vmcnt(0)
	v_pk_mul_f32 v[26:27], v[26:27], v[52:53] op_sel_hi:[1,0]
	v_add_u32_e32 v30, 0x410, v49
	ds_write2_b32 v30, v26, v27 offset1:1
	v_pk_mul_f32 v[26:27], v[28:29], v[52:53] op_sel_hi:[1,0]
	v_add_u32_e32 v28, 0x418, v49
	s_and_b64 vcc, exec, s[4:5]
	ds_write2_b32 v28, v26, v27 offset1:1
	s_cbranch_vccnz .LBB0_593
	s_ashr_i32 s19, s18, 31
	v_lshl_add_u64 v[26:27], s[18:19], 0, v[16:17]
	v_lshl_add_u64 v[26:27], v[26:27], 2, s[10:11]
	v_mov_b32_e32 v28, v124
	v_mov_b32_e32 v50, v125
	s_waitcnt vmcnt(1)
	v_pk_mul_f32 v[22:23], v[22:23], v[28:29] op_sel_hi:[1,0]
	v_pk_mul_f32 v[24:25], v[24:25], v[28:29] op_sel_hi:[1,0]
.LBB0_593:
	v_add_u32_e32 v26, 0x820, v49
	ds_write2_b32 v26, v22, v23 offset1:1
	v_add_u32_e32 v22, 0x828, v49
	ds_write2_b32 v22, v24, v25 offset1:1
	s_waitcnt vmcnt(0)
	v_pk_mul_f32 v[18:19], v[18:19], v[50:51] op_sel_hi:[1,0]
	v_add_u32_e32 v22, 0xc30, v49
	ds_write2_b32 v22, v18, v19 offset1:1
	v_pk_mul_f32 v[18:19], v[20:21], v[50:51] op_sel_hi:[1,0]
	v_add_u32_e32 v20, 0xc38, v49
	ds_write2_b32 v20, v18, v19 offset1:1
	v_mov_b32_e32 v18, 1.0
	s_and_b64 vcc, exec, s[4:5]
	v_mov_b32_e32 v20, 1.0
	s_cbranch_vccnz .LBB0_595
	s_ashr_i32 s19, s18, 31
	v_lshl_add_u64 v[20:21], s[18:19], 0, v[16:17]
	v_lshl_add_u64 v[20:21], v[20:21], 2, s[10:11]
	v_mov_b32_e32 v22, v126
	s_waitcnt vmcnt(0)
	v_pk_mul_f32 v[12:13], v[12:13], v[22:23] op_sel_hi:[1,0]
	v_mov_b32_e32 v20, v127
	v_pk_mul_f32 v[14:15], v[14:15], v[22:23] op_sel_hi:[1,0]
; #define LAS __attribute__((address_space(3)))
; template <bool PERMUTE, bool BLOCKED = false>
; __device__ __forceinline__ void cvt_tile64(const float* W, int K, int N, bf16* WT, int ldo, const float* gk, LAS float* scr, int tile, int lane) {
;     ...
; #pragma unroll
;     for (int hh = 0; hh < 2; ++hh) {
;         f32x4 v[8];
; #pragma unroll
;         for (int i = 0; i < 8; ++i) v[i] = *(const f32x4*)(W + (size_t)(k0 + 32 * hh + 4 * i + lk) * N + n0 + ln);
; #pragma unroll
;         for (int i = 0; i < 8; ++i) { const int kk = 32 * hh + 4 * i + lk; const float g = gk ? gk[k0 + kk] : 1.0f; LAS float* d = scr + kk * 65 + ln;
;             d[0] = v[i][0] * g; d[1] = v[i][1] * g; d[2] = v[i][2] * g; d[3] = v[i][3] * g; }
;     }
.LBB0_595:
	v_add_u32_e32 v19, 0x1040, v49
	ds_write2_b32 v19, v12, v13 offset1:1
	v_add_u32_e32 v12, 0x1048, v49
	ds_write2_b32 v12, v14, v15 offset1:1
	s_waitcnt vmcnt(0)
	v_pk_mul_f32 v[8:9], v[8:9], v[20:21] op_sel_hi:[1,0]
	v_add_u32_e32 v12, 0x1450, v49
	ds_write2_b32 v12, v8, v9 offset1:1
	v_pk_mul_f32 v[8:9], v[10:11], v[20:21] op_sel_hi:[1,0]
	v_add_u32_e32 v10, 0x1458, v49
	s_and_b64 vcc, exec, s[4:5]
	ds_write2_b32 v10, v8, v9 offset1:1
	s_cbranch_vccnz .LBB0_597
	s_ashr_i32 s19, s18, 31
	v_lshl_add_u64 v[8:9], s[18:19], 0, v[16:17]
	v_lshl_add_u64 v[8:9], v[8:9], 2, s[10:11]
	v_mov_b32_e32 v10, v178
	v_mov_b32_e32 v18, v179
	s_waitcnt vmcnt(1)
	v_pk_mul_f32 v[4:5], v[4:5], v[10:11] op_sel_hi:[1,0]
	v_pk_mul_f32 v[6:7], v[6:7], v[10:11] op_sel_hi:[1,0]
.LBB0_597:
	v_add_u32_e32 v8, 0x1860, v49
	ds_write2_b32 v8, v4, v5 offset1:1
	v_add_u32_e32 v4, 0x1868, v49
	ds_write2_b32 v4, v6, v7 offset1:1
	s_waitcnt vmcnt(0)
	v_pk_mul_f32 v[0:1], v[0:1], v[18:19] op_sel_hi:[1,0]
	v_add_u32_e32 v4, 0x1c70, v49
	ds_write2_b32 v4, v0, v1 offset1:1
	v_pk_mul_f32 v[0:1], v[2:3], v[18:19] op_sel_hi:[1,0]
	v_add_u32_e32 v2, 0x1c78, v49
	ds_write2_b32 v2, v0, v1 offset1:1
	v_or_b32_e32 v0, 32, v48
	v_or_b32_e32 v4, 60, v48
	v_ashrrev_i32_e32 v1, 31, v0
	v_ashrrev_i32_e32 v5, 31, v4
	v_lshlrev_b64 v[0:1], 16, v[0:1]
	v_lshlrev_b64 v[4:5], 16, v[4:5]
	v_lshl_add_u64 v[0:1], v[46:47], 0, v[0:1]
	v_lshl_add_u64 v[4:5], v[46:47], 0, v[4:5]
	global_load_dwordx4 v[26:29], v[0:1], off
	s_and_b64 vcc, exec, s[4:5]
	global_load_dwordx4 v[4:7], v[4:5], off
	v_or_b32_e32 v0, 36, v48
	v_ashrrev_i32_e32 v1, 31, v0
	v_lshlrev_b64 v[0:1], 16, v[0:1]
	v_lshl_add_u64 v[0:1], v[46:47], 0, v[0:1]
	global_load_dwordx4 v[30:33], v[0:1], off
	v_or_b32_e32 v0, 40, v48
	v_ashrrev_i32_e32 v1, 31, v0
	v_lshlrev_b64 v[0:1], 16, v[0:1]
	v_lshl_add_u64 v[0:1], v[46:47], 0, v[0:1]
	global_load_dwordx4 v[18:21], v[0:1], off
	v_or_b32_e32 v0, 44, v48
	v_ashrrev_i32_e32 v1, 31, v0
	v_lshlrev_b64 v[0:1], 16, v[0:1]
	v_lshl_add_u64 v[0:1], v[46:47], 0, v[0:1]
	global_load_dwordx4 v[22:25], v[0:1], off
	v_or_b32_e32 v0, 48, v48
	v_ashrrev_i32_e32 v1, 31, v0
	v_lshlrev_b64 v[0:1], 16, v[0:1]
	v_lshl_add_u64 v[0:1], v[46:47], 0, v[0:1]
	global_load_dwordx4 v[8:11], v[0:1], off
	v_or_b32_e32 v0, 52, v48
	v_ashrrev_i32_e32 v1, 31, v0
	v_lshlrev_b64 v[0:1], 16, v[0:1]
	v_lshl_add_u64 v[0:1], v[46:47], 0, v[0:1]
	global_load_dwordx4 v[12:15], v[0:1], off
	v_or_b32_e32 v0, 56, v48
	v_ashrrev_i32_e32 v1, 31, v0
	v_lshlrev_b64 v[0:1], 16, v[0:1]
	v_lshl_add_u64 v[0:1], v[46:47], 0, v[0:1]
	global_load_dwordx4 v[0:3], v[0:1], off
	v_mov_b32_e32 v46, 1.0
	v_mov_b32_e32 v48, 1.0
	s_cbranch_vccnz .LBB0_599
	s_ashr_i32 s19, s18, 31
	v_lshl_add_u64 v[64:65], s[18:19], 0, v[16:17]
	v_lshl_add_u64 v[64:65], v[64:65], 2, s[10:11]
	v_mov_b32_e32 v48, v180
	s_waitcnt vmcnt(0)
	v_pk_mul_f32 v[26:27], v[26:27], v[48:49] op_sel_hi:[1,0]
	v_pk_mul_f32 v[28:29], v[28:29], v[48:49] op_sel_hi:[1,0]
	v_mov_b32_e32 v48, v181
.LBB0_599:
	v_add_u32_e32 v47, 0x2080, v49
	s_waitcnt vmcnt(7)
	ds_write2_b32 v47, v26, v27 offset1:1
	v_add_u32_e32 v26, 0x2088, v49
	ds_write2_b32 v26, v28, v29 offset1:1
	s_waitcnt vmcnt(0)
	v_pk_mul_f32 v[26:27], v[30:31], v[48:49] op_sel_hi:[1,0]
	v_add_u32_e32 v28, 0x2490, v49
	ds_write2_b32 v28, v26, v27 offset1:1
	v_pk_mul_f32 v[26:27], v[32:33], v[48:49] op_sel_hi:[1,0]
	v_add_u32_e32 v28, 0x2498, v49
	s_and_b64 vcc, exec, s[4:5]
	ds_write2_b32 v28, v26, v27 offset1:1
	s_cbranch_vccnz .LBB0_601
	s_ashr_i32 s19, s18, 31
	v_lshl_add_u64 v[26:27], s[18:19], 0, v[16:17]
	v_lshl_add_u64 v[26:27], v[26:27], 2, s[10:11]
	v_mov_b32_e32 v28, v182
	v_mov_b32_e32 v46, v183
	s_waitcnt vmcnt(1)
	v_pk_mul_f32 v[18:19], v[18:19], v[28:29] op_sel_hi:[1,0]
	v_pk_mul_f32 v[20:21], v[20:21], v[28:29] op_sel_hi:[1,0]
.LBB0_601:
	v_add_u32_e32 v26, 0x28a0, v49
	ds_write2_b32 v26, v18, v19 offset1:1
	v_add_u32_e32 v18, 0x28a8, v49
	ds_write2_b32 v18, v20, v21 offset1:1
	s_waitcnt vmcnt(0)
	v_pk_mul_f32 v[18:19], v[22:23], v[46:47] op_sel_hi:[1,0]
	v_add_u32_e32 v20, 0x2cb0, v49
	ds_write2_b32 v20, v18, v19 offset1:1
	v_pk_mul_f32 v[18:19], v[24:25], v[46:47] op_sel_hi:[1,0]
	v_add_u32_e32 v20, 0x2cb8, v49
	s_and_b64 vcc, exec, s[4:5]
	ds_write2_b32 v20, v18, v19 offset1:1
	s_cbranch_vccnz .LBB0_603
	s_ashr_i32 s19, s18, 31
	v_lshl_add_u64 v[18:19], s[18:19], 0, v[16:17]
	v_lshl_add_u64 v[18:19], v[18:19], 2, s[10:11]
	v_mov_b32_e32 v20, v184
	s_waitcnt vmcnt(0)
	v_pk_mul_f32 v[8:9], v[8:9], v[20:21] op_sel_hi:[1,0]
	v_mov_b32_e32 v18, v185
	v_pk_mul_f32 v[10:11], v[10:11], v[20:21] op_sel_hi:[1,0]
	s_branch .LBB0_604

; #define LAS __attribute__((address_space(3)))
; template <bool PERMUTE, bool BLOCKED = false>
; __device__ __forceinline__ void cvt_tile64(const float* W, int K, int N, bf16* WT, int ldo, const float* gk, LAS float* scr, int tile, int lane) {
;     ...
;         for (int i = 0; i < 8; ++i) { const int kk = 32 * hh + 4 * i + lk; const float g = gk ? gk[k0 + kk] : 1.0f; LAS float* d = scr + kk * 65 + ln;
;             d[0] = v[i][0] * g; d[1] = v[i][1] * g; d[2] = v[i][2] * g; d[3] = v[i][3] * g; }
;     }
.LBB0_604:
	v_add_u32_e32 v19, 0x30c0, v49
	ds_write2_b32 v19, v8, v9 offset1:1
	v_add_u32_e32 v8, 0x30c8, v49
	ds_write2_b32 v8, v10, v11 offset1:1
	s_waitcnt vmcnt(0)
	v_pk_mul_f32 v[8:9], v[12:13], v[18:19] op_sel_hi:[1,0]
	v_add_u32_e32 v10, 0x34d0, v49
	ds_write2_b32 v10, v8, v9 offset1:1
	v_pk_mul_f32 v[8:9], v[14:15], v[18:19] op_sel_hi:[1,0]
	v_add_u32_e32 v10, 0x34d8, v49
	s_and_b64 vcc, exec, s[14:15]
	ds_write2_b32 v10, v8, v9 offset1:1
	s_cbranch_vccz .LBB0_611
	s_ashr_i32 s19, s18, 31
	v_lshl_add_u64 v[8:9], s[18:19], 0, v[16:17]
	v_lshl_add_u64 v[8:9], v[8:9], 2, s[10:11]
	v_mov_b32_e32 v10, v186
	s_nop 0
	v_mov_b32_e32 v8, v187
	s_waitcnt vmcnt(1)
	v_pk_mul_f32 v[0:1], v[0:1], v[10:11] op_sel_hi:[1,0]
	v_pk_mul_f32 v[2:3], v[2:3], v[10:11] op_sel_hi:[1,0]
	s_cbranch_execnz .LBB0_607

; #define LAS __attribute__((address_space(3)))
; template <bool PERMUTE, bool BLOCKED = false>
; __device__ __forceinline__ void cvt_tile64(const float* W, int K, int N, bf16* WT, int ldo, const float* gk, LAS float* scr, int tile, int lane) {
;     const int nblk = N >> 6, kb = tile / nblk, nb = tile - kb * nblk, k0 = 64 * kb, n0 = 64 * nb;
;     const int lk = lane >> 4, ln = (lane & 15) * 4;
;     ...
;     {
;         f32x4 v[16];
; #pragma unroll
;         for (int i = 0; i < 16; ++i) v[i] = *(const f32x4*)(W + (size_t)(k0 + 4 * i + lk) * N + n0 + ln);
; #pragma unroll
;         for (int i = 0; i < 16; ++i) { const int kk = 4 * i + lk; const float g = gk ? gk[k0 + kk] : 1.0f; LAS float* d = scr + kk * 65 + ln;
;             d[0] = v[i][0] * g; d[1] = v[i][1] * g; d[2] = v[i][2] * g; d[3] = v[i][3] * g; }
;     }
;     ...
; #pragma unroll
;     for (int hh = 0; hh < 2; ++hh) {
;         f32x4 v[8];
; #pragma unroll
;         for (int i = 0; i < 8; ++i) v[i] = *(const f32x4*)(W + (size_t)(k0 + 32 * hh + 4 * i + lk) * N + n0 + ln);
; #pragma unroll
;         for (int i = 0; i < 8; ++i) { const int kk = 32 * hh + 4 * i + lk; const float g = gk ? gk[k0 + kk] : 1.0f; LAS float* d = scr + kk * 65 + ln;
;             d[0] = v[i][0] * g; d[1] = v[i][1] * g; d[2] = v[i][2] * g; d[3] = v[i][3] * g; }
;     }
; __device__ __forceinline__ void cvt_item(const CvtCtx& c, int batch, int wi, LAS float* scr, int wave, int lane) {
;     ...
;     if (wi < CVT_OUT) { cvt_tile64<false>(c.w_out + (size_t)l * DM * DM, DM, DM, c.WoutT + (size_t)l * DM * DM, DM, nullptr, scr, 8 * wi + wave, lane); return; } wi -= CVT_OUT;
;     if (wi < CVT_UP) { cvt_tile64<false>(c.w_up + (size_t)l * DM * DFF, DM, DFF, c.WupT + (size_t)l * DFF * DM, DM, c.g_mlp + l * DM, scr, 8 * wi + wave, lane); return; } wi -= CVT_UP;
.LBB0_672:
	s_andn2_b64 vcc, exec, s[0:1]
	s_cbranch_vccnz .LBB0_692
	s_add_i32 s0, s13, 0xfffff000
	s_ashr_i32 s1, s0, 31
	s_lshr_b32 s1, s1, 24
	s_add_i32 s0, s0, s1
	s_ashr_i32 s0, s0, 8
	s_lshl_b32 s20, s0, 6
	s_lshl_b32 s22, s0, 14
	s_add_i32 s0, s12, s16
	s_sub_i32 s0, s0, s22
	v_or_b32_e32 v48, s20, v16
	s_add_i32 s0, s0, 0x128000
	v_or_b32_e32 v2, 4, v48
	s_ashr_i32 s1, s0, 31
	v_ashrrev_i32_e32 v49, 31, v48
	v_ashrrev_i32_e32 v3, 31, v2
	v_lshl_add_u64 v[46:47], s[0:1], 2, v[38:39]
	v_lshlrev_b64 v[0:1], 16, v[48:49]
	v_lshlrev_b64 v[2:3], 16, v[2:3]
	v_lshl_add_u64 v[0:1], v[46:47], 0, v[0:1]
	v_lshl_add_u64 v[2:3], v[46:47], 0, v[2:3]
	global_load_dwordx4 v[30:33], v[0:1], off
	global_load_dwordx4 v[26:29], v[2:3], off
	v_or_b32_e32 v0, 8, v48
	v_or_b32_e32 v2, 12, v48
	v_ashrrev_i32_e32 v1, 31, v0
	v_ashrrev_i32_e32 v3, 31, v2
	v_lshlrev_b64 v[0:1], 16, v[0:1]
	v_lshlrev_b64 v[2:3], 16, v[2:3]
	v_lshl_add_u64 v[0:1], v[46:47], 0, v[0:1]
	v_lshl_add_u64 v[2:3], v[46:47], 0, v[2:3]
	global_load_dwordx4 v[22:25], v[0:1], off
	global_load_dwordx4 v[18:21], v[2:3], off
	v_or_b32_e32 v0, 16, v48
	v_or_b32_e32 v2, 20, v48
	v_ashrrev_i32_e32 v1, 31, v0
	v_ashrrev_i32_e32 v3, 31, v2
	v_lshlrev_b64 v[0:1], 16, v[0:1]
	v_lshlrev_b64 v[2:3], 16, v[2:3]
	v_lshl_add_u64 v[0:1], v[46:47], 0, v[0:1]
	v_lshl_add_u64 v[2:3], v[46:47], 0, v[2:3]
	global_load_dwordx4 v[12:15], v[0:1], off
	global_load_dwordx4 v[8:11], v[2:3], off
	v_or_b32_e32 v0, 24, v48
	v_or_b32_e32 v2, 28, v48
	v_ashrrev_i32_e32 v1, 31, v0
	v_ashrrev_i32_e32 v3, 31, v2
	v_lshlrev_b64 v[0:1], 16, v[0:1]
	v_lshlrev_b64 v[2:3], 16, v[2:3]
	v_lshl_add_u64 v[0:1], v[46:47], 0, v[0:1]
	v_lshl_add_u64 v[2:3], v[46:47], 0, v[2:3]
	global_load_dwordx4 v[4:7], v[0:1], off
	s_nop 0
	global_load_dwordx4 v[0:3], v[2:3], off
	v_cndmask_b32_e64 v52, 0, 1, s[18:19]
	v_mov_b32_e32 v50, 1.0
	v_cmp_ne_u32_e64 s[10:11], 1, v52
	s_andn2_b64 vcc, exec, s[18:19]
	v_mov_b32_e32 v52, 1.0
	s_cbranch_vccnz .LBB0_675
	v_lshl_add_u64 v[64:65], v[48:49], 2, s[14:15]
	global_load_dword v110, v[64:65], off offset:16
	global_load_dword v124, v[64:65], off offset:32
	global_load_dword v125, v[64:65], off offset:48
	global_load_dword v126, v[64:65], off offset:64
	global_load_dword v127, v[64:65], off offset:80
	global_load_dword v178, v[64:65], off offset:96
	global_load_dword v179, v[64:65], off offset:112
	global_load_dword v180, v[64:65], off offset:128
	global_load_dword v181, v[64:65], off offset:144
	global_load_dword v182, v[64:65], off offset:160
	global_load_dword v183, v[64:65], off offset:176
	global_load_dword v184, v[64:65], off offset:192
	global_load_dword v185, v[64:65], off offset:208
	global_load_dword v186, v[64:65], off offset:224
	global_load_dword v187, v[64:65], off offset:240
	global_load_dword v52, v[64:65], off
	s_waitcnt vmcnt(0)
	s_ashr_i32 s21, s20, 31
	v_lshl_add_u64 v[64:65], s[20:21], 0, v[16:17]
	v_lshl_add_u64 v[64:65], v[64:65], 2, s[14:15]
	s_waitcnt vmcnt(0)
	v_pk_mul_f32 v[30:31], v[30:31], v[52:53] op_sel_hi:[1,0]
	v_pk_mul_f32 v[32:33], v[32:33], v[52:53] op_sel_hi:[1,0]
	v_mov_b32_e32 v52, v110
.LBB0_675:
	v_add_u32_e32 v49, v51, v53
	s_waitcnt vmcnt(7)
	ds_write2_b32 v49, v30, v31 offset1:1
	ds_write2_b32 v49, v32, v33 offset0:2 offset1:3
	s_waitcnt vmcnt(0)
	v_pk_mul_f32 v[26:27], v[26:27], v[52:53] op_sel_hi:[1,0]
	v_add_u32_e32 v30, 0x410, v49
	ds_write2_b32 v30, v26, v27 offset1:1
	v_pk_mul_f32 v[26:27], v[28:29], v[52:53] op_sel_hi:[1,0]
	v_add_u32_e32 v28, 0x418, v49
	s_and_b64 vcc, exec, s[10:11]
	ds_write2_b32 v28, v26, v27 offset1:1
	s_cbranch_vccnz .LBB0_677
	s_ashr_i32 s21, s20, 31
	v_lshl_add_u64 v[26:27], s[20:21], 0, v[16:17]
	v_lshl_add_u64 v[26:27], v[26:27], 2, s[14:15]
	v_mov_b32_e32 v28, v124
	v_mov_b32_e32 v50, v125
	s_waitcnt vmcnt(1)
	v_pk_mul_f32 v[22:23], v[22:23], v[28:29] op_sel_hi:[1,0]
	v_pk_mul_f32 v[24:25], v[24:25], v[28:29] op_sel_hi:[1,0]
.LBB0_677:
	v_add_u32_e32 v26, 0x820, v49
	ds_write2_b32 v26, v22, v23 offset1:1
	v_add_u32_e32 v22, 0x828, v49
	ds_write2_b32 v22, v24, v25 offset1:1
	s_waitcnt vmcnt(0)
	v_pk_mul_f32 v[18:19], v[18:19], v[50:51] op_sel_hi:[1,0]
	v_add_u32_e32 v22, 0xc30, v49
	ds_write2_b32 v22, v18, v19 offset1:1
	v_pk_mul_f32 v[18:19], v[20:21], v[50:51] op_sel_hi:[1,0]
	v_add_u32_e32 v20, 0xc38, v49
	ds_write2_b32 v20, v18, v19 offset1:1
	v_mov_b32_e32 v18, 1.0
	s_and_b64 vcc, exec, s[10:11]
	v_mov_b32_e32 v20, 1.0
	s_cbranch_vccnz .LBB0_679
	s_ashr_i32 s21, s20, 31
	v_lshl_add_u64 v[20:21], s[20:21], 0, v[16:17]
	v_lshl_add_u64 v[20:21], v[20:21], 2, s[14:15]
	v_mov_b32_e32 v22, v126
	s_waitcnt vmcnt(0)
	v_pk_mul_f32 v[12:13], v[12:13], v[22:23] op_sel_hi:[1,0]
	v_mov_b32_e32 v20, v127
	v_pk_mul_f32 v[14:15], v[14:15], v[22:23] op_sel_hi:[1,0]
; #define LAS __attribute__((address_space(3)))
; template <bool PERMUTE, bool BLOCKED = false>
; __device__ __forceinline__ void cvt_tile64(const float* W, int K, int N, bf16* WT, int ldo, const float* gk, LAS float* scr, int tile, int lane) {
;     ...
; #pragma unroll
;     for (int hh = 0; hh < 2; ++hh) {
;         f32x4 v[8];
; #pragma unroll
;         for (int i = 0; i < 8; ++i) v[i] = *(const f32x4*)(W + (size_t)(k0 + 32 * hh + 4 * i + lk) * N + n0 + ln);
; #pragma unroll
;         for (int i = 0; i < 8; ++i) { const int kk = 32 * hh + 4 * i + lk; const float g = gk ? gk[k0 + kk] : 1.0f; LAS float* d = scr + kk * 65 + ln;
;             d[0] = v[i][0] * g; d[1] = v[i][1] * g; d[2] = v[i][2] * g; d[3] = v[i][3] * g; }
;     }
.LBB0_679:
	v_add_u32_e32 v19, 0x1040, v49
	ds_write2_b32 v19, v12, v13 offset1:1
	v_add_u32_e32 v12, 0x1048, v49
	ds_write2_b32 v12, v14, v15 offset1:1
	s_waitcnt vmcnt(0)
	v_pk_mul_f32 v[8:9], v[8:9], v[20:21] op_sel_hi:[1,0]
	v_add_u32_e32 v12, 0x1450, v49
	ds_write2_b32 v12, v8, v9 offset1:1
	v_pk_mul_f32 v[8:9], v[10:11], v[20:21] op_sel_hi:[1,0]
	v_add_u32_e32 v10, 0x1458, v49
	s_and_b64 vcc, exec, s[10:11]
	ds_write2_b32 v10, v8, v9 offset1:1
	s_cbranch_vccnz .LBB0_681
	s_ashr_i32 s21, s20, 31
	v_lshl_add_u64 v[8:9], s[20:21], 0, v[16:17]
	v_lshl_add_u64 v[8:9], v[8:9], 2, s[14:15]
	v_mov_b32_e32 v10, v178
	v_mov_b32_e32 v18, v179
	s_waitcnt vmcnt(1)
	v_pk_mul_f32 v[4:5], v[4:5], v[10:11] op_sel_hi:[1,0]
	v_pk_mul_f32 v[6:7], v[6:7], v[10:11] op_sel_hi:[1,0]
.LBB0_681:
	v_add_u32_e32 v8, 0x1860, v49
	ds_write2_b32 v8, v4, v5 offset1:1
	v_add_u32_e32 v4, 0x1868, v49
	ds_write2_b32 v4, v6, v7 offset1:1
	s_waitcnt vmcnt(0)
	v_pk_mul_f32 v[0:1], v[0:1], v[18:19] op_sel_hi:[1,0]
	v_add_u32_e32 v4, 0x1c70, v49
	ds_write2_b32 v4, v0, v1 offset1:1
	v_pk_mul_f32 v[0:1], v[2:3], v[18:19] op_sel_hi:[1,0]
	v_add_u32_e32 v2, 0x1c78, v49
	ds_write2_b32 v2, v0, v1 offset1:1
	v_or_b32_e32 v0, 32, v48
	v_or_b32_e32 v4, 60, v48
	v_ashrrev_i32_e32 v1, 31, v0
	v_ashrrev_i32_e32 v5, 31, v4
	v_lshlrev_b64 v[0:1], 16, v[0:1]
	v_lshlrev_b64 v[4:5], 16, v[4:5]
	v_lshl_add_u64 v[0:1], v[46:47], 0, v[0:1]
	v_lshl_add_u64 v[4:5], v[46:47], 0, v[4:5]
	global_load_dwordx4 v[26:29], v[0:1], off
	s_and_b64 vcc, exec, s[10:11]
	global_load_dwordx4 v[4:7], v[4:5], off
	v_or_b32_e32 v0, 36, v48
	v_ashrrev_i32_e32 v1, 31, v0
	v_lshlrev_b64 v[0:1], 16, v[0:1]
	v_lshl_add_u64 v[0:1], v[46:47], 0, v[0:1]
	global_load_dwordx4 v[30:33], v[0:1], off
	v_or_b32_e32 v0, 40, v48
	v_ashrrev_i32_e32 v1, 31, v0
	v_lshlrev_b64 v[0:1], 16, v[0:1]
	v_lshl_add_u64 v[0:1], v[46:47], 0, v[0:1]
	global_load_dwordx4 v[18:21], v[0:1], off
	v_or_b32_e32 v0, 44, v48
	v_ashrrev_i32_e32 v1, 31, v0
	v_lshlrev_b64 v[0:1], 16, v[0:1]
	v_lshl_add_u64 v[0:1], v[46:47], 0, v[0:1]
	global_load_dwordx4 v[22:25], v[0:1], off
	v_or_b32_e32 v0, 48, v48
	v_ashrrev_i32_e32 v1, 31, v0
	v_lshlrev_b64 v[0:1], 16, v[0:1]
	v_lshl_add_u64 v[0:1], v[46:47], 0, v[0:1]
	global_load_dwordx4 v[8:11], v[0:1], off
	v_or_b32_e32 v0, 52, v48
	v_ashrrev_i32_e32 v1, 31, v0
	v_lshlrev_b64 v[0:1], 16, v[0:1]
	v_lshl_add_u64 v[0:1], v[46:47], 0, v[0:1]
	global_load_dwordx4 v[12:15], v[0:1], off
	v_or_b32_e32 v0, 56, v48
	v_ashrrev_i32_e32 v1, 31, v0
	v_lshlrev_b64 v[0:1], 16, v[0:1]
	v_lshl_add_u64 v[0:1], v[46:47], 0, v[0:1]
	global_load_dwordx4 v[0:3], v[0:1], off
	v_mov_b32_e32 v46, 1.0
	v_mov_b32_e32 v48, 1.0
	s_cbranch_vccnz .LBB0_683
	s_ashr_i32 s21, s20, 31
	v_lshl_add_u64 v[64:65], s[20:21], 0, v[16:17]
	v_lshl_add_u64 v[64:65], v[64:65], 2, s[14:15]
	v_mov_b32_e32 v48, v180
	s_waitcnt vmcnt(0)
	v_pk_mul_f32 v[26:27], v[26:27], v[48:49] op_sel_hi:[1,0]
	v_pk_mul_f32 v[28:29], v[28:29], v[48:49] op_sel_hi:[1,0]
	v_mov_b32_e32 v48, v181
.LBB0_683:
	v_add_u32_e32 v47, 0x2080, v49
	s_waitcnt vmcnt(7)
	ds_write2_b32 v47, v26, v27 offset1:1
	v_add_u32_e32 v26, 0x2088, v49
	ds_write2_b32 v26, v28, v29 offset1:1
	s_waitcnt vmcnt(0)
	v_pk_mul_f32 v[26:27], v[30:31], v[48:49] op_sel_hi:[1,0]
	v_add_u32_e32 v28, 0x2490, v49
	ds_write2_b32 v28, v26, v27 offset1:1
	v_pk_mul_f32 v[26:27], v[32:33], v[48:49] op_sel_hi:[1,0]
	v_add_u32_e32 v28, 0x2498, v49
	s_and_b64 vcc, exec, s[10:11]
	ds_write2_b32 v28, v26, v27 offset1:1
	s_cbranch_vccnz .LBB0_685
	s_ashr_i32 s21, s20, 31
	v_lshl_add_u64 v[26:27], s[20:21], 0, v[16:17]
	v_lshl_add_u64 v[26:27], v[26:27], 2, s[14:15]
	v_mov_b32_e32 v28, v182
	v_mov_b32_e32 v46, v183
	s_waitcnt vmcnt(1)
	v_pk_mul_f32 v[18:19], v[18:19], v[28:29] op_sel_hi:[1,0]
	v_pk_mul_f32 v[20:21], v[20:21], v[28:29] op_sel_hi:[1,0]
.LBB0_685:
	v_add_u32_e32 v26, 0x28a0, v49
	ds_write2_b32 v26, v18, v19 offset1:1
	v_add_u32_e32 v18, 0x28a8, v49
	ds_write2_b32 v18, v20, v21 offset1:1
	s_waitcnt vmcnt(0)
	v_pk_mul_f32 v[18:19], v[22:23], v[46:47] op_sel_hi:[1,0]
	v_add_u32_e32 v20, 0x2cb0, v49
	ds_write2_b32 v20, v18, v19 offset1:1
	v_pk_mul_f32 v[18:19], v[24:25], v[46:47] op_sel_hi:[1,0]
	v_add_u32_e32 v20, 0x2cb8, v49
	s_and_b64 vcc, exec, s[10:11]
	ds_write2_b32 v20, v18, v19 offset1:1
	s_cbranch_vccnz .LBB0_687
	s_ashr_i32 s21, s20, 31
	v_lshl_add_u64 v[18:19], s[20:21], 0, v[16:17]
	v_lshl_add_u64 v[18:19], v[18:19], 2, s[14:15]
	v_mov_b32_e32 v20, v184
	s_waitcnt vmcnt(0)
	v_pk_mul_f32 v[8:9], v[8:9], v[20:21] op_sel_hi:[1,0]
	v_mov_b32_e32 v18, v185
	v_pk_mul_f32 v[10:11], v[10:11], v[20:21] op_sel_hi:[1,0]
	s_branch .LBB0_688

; #define LAS __attribute__((address_space(3)))
; template <bool PERMUTE, bool BLOCKED = false>
; __device__ __forceinline__ void cvt_tile64(const float* W, int K, int N, bf16* WT, int ldo, const float* gk, LAS float* scr, int tile, int lane) {
;     ...
;         for (int i = 0; i < 8; ++i) { const int kk = 32 * hh + 4 * i + lk; const float g = gk ? gk[k0 + kk] : 1.0f; LAS float* d = scr + kk * 65 + ln;
;             d[0] = v[i][0] * g; d[1] = v[i][1] * g; d[2] = v[i][2] * g; d[3] = v[i][3] * g; }
;     }
.LBB0_688:
	v_add_u32_e32 v19, 0x30c0, v49
	ds_write2_b32 v19, v8, v9 offset1:1
	v_add_u32_e32 v8, 0x30c8, v49
	ds_write2_b32 v8, v10, v11 offset1:1
	s_waitcnt vmcnt(0)
	v_pk_mul_f32 v[8:9], v[12:13], v[18:19] op_sel_hi:[1,0]
	v_add_u32_e32 v10, 0x34d0, v49
	ds_write2_b32 v10, v8, v9 offset1:1
	v_pk_mul_f32 v[8:9], v[14:15], v[18:19] op_sel_hi:[1,0]
	v_add_u32_e32 v10, 0x34d8, v49
	s_and_b64 vcc, exec, s[18:19]
	ds_write2_b32 v10, v8, v9 offset1:1
	s_cbranch_vccz .LBB0_695
	s_ashr_i32 s21, s20, 31
	v_lshl_add_u64 v[8:9], s[20:21], 0, v[16:17]
	v_lshl_add_u64 v[8:9], v[8:9], 2, s[14:15]
	v_mov_b32_e32 v10, v186
	s_nop 0
	v_mov_b32_e32 v8, v187
	s_waitcnt vmcnt(1)
	v_pk_mul_f32 v[0:1], v[0:1], v[10:11] op_sel_hi:[1,0]
	v_pk_mul_f32 v[2:3], v[2:3], v[10:11] op_sel_hi:[1,0]
	s_cbranch_execnz .LBB0_691

; #define LAS __attribute__((address_space(3)))
; template <bool PERMUTE, bool BLOCKED = false>
; __device__ __forceinline__ void cvt_tile64(const float* W, int K, int N, bf16* WT, int ldo, const float* gk, LAS float* scr, int tile, int lane) {
;     const int nblk = N >> 6, kb = tile / nblk, nb = tile - kb * nblk, k0 = 64 * kb, n0 = 64 * nb;
;     const int lk = lane >> 4, ln = (lane & 15) * 4;
;     ...
;     {
;         f32x4 v[16];
; #pragma unroll
;         for (int i = 0; i < 16; ++i) v[i] = *(const f32x4*)(W + (size_t)(k0 + 4 * i + lk) * N + n0 + ln);
; #pragma unroll
;         for (int i = 0; i < 16; ++i) { const int kk = 4 * i + lk; const float g = gk ? gk[k0 + kk] : 1.0f; LAS float* d = scr + kk * 65 + ln;
;             d[0] = v[i][0] * g; d[1] = v[i][1] * g; d[2] = v[i][2] * g; d[3] = v[i][3] * g; }
;     }
;     ...
; #pragma unroll
;     for (int hh = 0; hh < 2; ++hh) {
;         f32x4 v[8];
; #pragma unroll
;         for (int i = 0; i < 8; ++i) v[i] = *(const f32x4*)(W + (size_t)(k0 + 32 * hh + 4 * i + lk) * N + n0 + ln);
; #pragma unroll
;         for (int i = 0; i < 8; ++i) { const int kk = 32 * hh + 4 * i + lk; const float g = gk ? gk[k0 + kk] : 1.0f; LAS float* d = scr + kk * 65 + ln;
; __device__ __forceinline__ void cvt_item(const CvtCtx& c, int batch, int wi, LAS float* scr, int wave, int lane) {
;     ...
;     if (wi < CVT_OUT) { cvt_tile64<false>(c.w_out + (size_t)l * DM * DM, DM, DM, c.WoutT + (size_t)l * DM * DM, DM, nullptr, scr, 8 * wi + wave, lane); return; } wi -= CVT_OUT;
;     if (wi < CVT_UP) { cvt_tile64<false>(c.w_up + (size_t)l * DM * DFF, DM, DFF, c.WupT + (size_t)l * DFF * DM, DM, c.g_mlp + l * DM, scr, 8 * wi + wave, lane); return; } wi -= CVT_UP;
.LBB0_726:
	s_andn2_b64 vcc, exec, s[0:1]
	s_cbranch_vccnz .LBB0_746
	s_add_i32 s0, s13, 0xfffff000
	s_ashr_i32 s1, s0, 31
	s_lshr_b32 s1, s1, 24
	s_add_i32 s0, s0, s1
	s_ashr_i32 s0, s0, 8
	s_lshl_b32 s18, s0, 6
	s_lshl_b32 s20, s0, 14
	s_add_i32 s0, s12, s16
	s_sub_i32 s0, s0, s20
	v_or_b32_e32 v48, s18, v16
	s_add_i32 s0, s0, 0x128000
	v_or_b32_e32 v2, 4, v48
	s_ashr_i32 s1, s0, 31
	v_ashrrev_i32_e32 v49, 31, v48
	v_ashrrev_i32_e32 v3, 31, v2
	v_lshl_add_u64 v[46:47], s[0:1], 2, v[38:39]
	v_lshlrev_b64 v[0:1], 16, v[48:49]
	v_lshlrev_b64 v[2:3], 16, v[2:3]
	v_lshl_add_u64 v[0:1], v[46:47], 0, v[0:1]
	v_lshl_add_u64 v[2:3], v[46:47], 0, v[2:3]
	global_load_dwordx4 v[30:33], v[0:1], off
	global_load_dwordx4 v[26:29], v[2:3], off
	v_or_b32_e32 v0, 8, v48
	v_or_b32_e32 v2, 12, v48
	v_ashrrev_i32_e32 v1, 31, v0
	v_ashrrev_i32_e32 v3, 31, v2
	v_lshlrev_b64 v[0:1], 16, v[0:1]
	v_lshlrev_b64 v[2:3], 16, v[2:3]
	v_lshl_add_u64 v[0:1], v[46:47], 0, v[0:1]
	v_lshl_add_u64 v[2:3], v[46:47], 0, v[2:3]
	global_load_dwordx4 v[22:25], v[0:1], off
	global_load_dwordx4 v[18:21], v[2:3], off
	v_or_b32_e32 v0, 16, v48
	v_or_b32_e32 v2, 20, v48
	v_ashrrev_i32_e32 v1, 31, v0
	v_ashrrev_i32_e32 v3, 31, v2
	v_lshlrev_b64 v[0:1], 16, v[0:1]
	v_lshlrev_b64 v[2:3], 16, v[2:3]
	v_lshl_add_u64 v[0:1], v[46:47], 0, v[0:1]
	v_lshl_add_u64 v[2:3], v[46:47], 0, v[2:3]
	global_load_dwordx4 v[12:15], v[0:1], off
	global_load_dwordx4 v[8:11], v[2:3], off
	v_or_b32_e32 v0, 24, v48
	v_or_b32_e32 v2, 28, v48
	v_ashrrev_i32_e32 v1, 31, v0
	v_ashrrev_i32_e32 v3, 31, v2
	v_lshlrev_b64 v[0:1], 16, v[0:1]
	v_lshlrev_b64 v[2:3], 16, v[2:3]
	v_lshl_add_u64 v[0:1], v[46:47], 0, v[0:1]
	v_lshl_add_u64 v[2:3], v[46:47], 0, v[2:3]
	global_load_dwordx4 v[4:7], v[0:1], off
	s_nop 0
	global_load_dwordx4 v[0:3], v[2:3], off
	v_cndmask_b32_e64 v52, 0, 1, s[14:15]
	v_mov_b32_e32 v50, 1.0
	v_cmp_ne_u32_e64 s[4:5], 1, v52
	s_andn2_b64 vcc, exec, s[14:15]
	v_mov_b32_e32 v52, 1.0
	s_cbranch_vccnz .LBB0_729
	v_lshl_add_u64 v[64:65], v[48:49], 2, s[10:11]
	global_load_dword v110, v[64:65], off offset:16
	global_load_dword v124, v[64:65], off offset:32
	global_load_dword v125, v[64:65], off offset:48
	global_load_dword v126, v[64:65], off offset:64
	global_load_dword v127, v[64:65], off offset:80
	global_load_dword v178, v[64:65], off offset:96
	global_load_dword v179, v[64:65], off offset:112
	global_load_dword v180, v[64:65], off offset:128
	global_load_dword v181, v[64:65], off offset:144
	global_load_dword v182, v[64:65], off offset:160
	global_load_dword v183, v[64:65], off offset:176
	global_load_dword v184, v[64:65], off offset:192
	global_load_dword v185, v[64:65], off offset:208
	global_load_dword v186, v[64:65], off offset:224
	global_load_dword v187, v[64:65], off offset:240
	global_load_dword v52, v[64:65], off
	s_waitcnt vmcnt(0)
	s_ashr_i32 s19, s18, 31
	v_lshl_add_u64 v[64:65], s[18:19], 0, v[16:17]
	v_lshl_add_u64 v[64:65], v[64:65], 2, s[10:11]
	s_waitcnt vmcnt(0)
	v_pk_mul_f32 v[30:31], v[30:31], v[52:53] op_sel_hi:[1,0]
	v_pk_mul_f32 v[32:33], v[32:33], v[52:53] op_sel_hi:[1,0]
	v_mov_b32_e32 v52, v110

; #define LAS __attribute__((address_space(3)))
; template <bool PERMUTE, bool BLOCKED = false>
; __device__ __forceinline__ void cvt_tile64(const float* W, int K, int N, bf16* WT, int ldo, const float* gk, LAS float* scr, int tile, int lane) {
;     const int nblk = N >> 6, kb = tile / nblk, nb = tile - kb * nblk, k0 = 64 * kb, n0 = 64 * nb;
;     const int lk = lane >> 4, ln = (lane & 15) * 4;
;     ...
;     {
;         f32x4 v[16];
; #pragma unroll
;         for (int i = 0; i < 16; ++i) v[i] = *(const f32x4*)(W + (size_t)(k0 + 4 * i + lk) * N + n0 + ln);
; #pragma unroll
;         for (int i = 0; i < 16; ++i) { const int kk = 4 * i + lk; const float g = gk ? gk[k0 + kk] : 1.0f; LAS float* d = scr + kk * 65 + ln;
;             d[0] = v[i][0] * g; d[1] = v[i][1] * g; d[2] = v[i][2] * g; d[3] = v[i][3] * g; }
;     }
;     ...
; #pragma unroll
;     for (int hh = 0; hh < 2; ++hh) {
;         f32x4 v[8];
; #pragma unroll
;         for (int i = 0; i < 8; ++i) v[i] = *(const f32x4*)(W + (size_t)(k0 + 32 * hh + 4 * i + lk) * N + n0 + ln);
; #pragma unroll
;         for (int i = 0; i < 8; ++i) { const int kk = 32 * hh + 4 * i + lk; const float g = gk ? gk[k0 + kk] : 1.0f; LAS float* d = scr + kk * 65 + ln;
;             d[0] = v[i][0] * g; d[1] = v[i][1] * g; d[2] = v[i][2] * g; d[3] = v[i][3] * g; }
;     }
; __device__ __forceinline__ void cvt_item(const CvtCtx& c, int batch, int wi, LAS float* scr, int wave, int lane) {
;     ...
;     if (wi < CVT_OUT) { cvt_tile64<false>(c.w_out + (size_t)l * DM * DM, DM, DM, c.WoutT + (size_t)l * DM * DM, DM, nullptr, scr, 8 * wi + wave, lane); return; } wi -= CVT_OUT;
;     if (wi < CVT_UP) { cvt_tile64<false>(c.w_up + (size_t)l * DM * DFF, DM, DFF, c.WupT + (size_t)l * DFF * DM, DM, c.g_mlp + l * DM, scr, 8 * wi + wave, lane); return; } wi -= CVT_UP;
.LBB0_814:
	s_andn2_b64 vcc, exec, s[0:1]
	s_cbranch_vccnz .LBB0_834
	s_add_i32 s0, s16, 0x8000
	s_ashr_i32 s1, s0, 31
	s_lshr_b32 s1, s1, 24
	s_add_i32 s0, s0, s1
	s_ashr_i32 s0, s0, 8
	s_lshl_b32 s18, s0, 6
	s_lshl_b32 s20, s0, 14
	s_sub_i32 s0, s13, s20
	v_or_b32_e32 v52, s18, v16
	s_add_i32 s0, s0, 0x200000
	v_or_b32_e32 v2, 4, v52
	s_ashr_i32 s1, s0, 31
	v_ashrrev_i32_e32 v53, 31, v52
	v_ashrrev_i32_e32 v3, 31, v2
	v_lshl_add_u64 v[50:51], s[0:1], 2, v[42:43]
	v_lshlrev_b64 v[0:1], 16, v[52:53]
	v_lshlrev_b64 v[2:3], 16, v[2:3]
	v_lshl_add_u64 v[0:1], v[50:51], 0, v[0:1]
	v_lshl_add_u64 v[2:3], v[50:51], 0, v[2:3]
	global_load_dwordx4 v[30:33], v[0:1], off
	global_load_dwordx4 v[26:29], v[2:3], off
	v_or_b32_e32 v0, 8, v52
	v_or_b32_e32 v2, 12, v52
	v_ashrrev_i32_e32 v1, 31, v0
	v_ashrrev_i32_e32 v3, 31, v2
	v_lshlrev_b64 v[0:1], 16, v[0:1]
	v_lshlrev_b64 v[2:3], 16, v[2:3]
	v_lshl_add_u64 v[0:1], v[50:51], 0, v[0:1]
	v_lshl_add_u64 v[2:3], v[50:51], 0, v[2:3]
	global_load_dwordx4 v[22:25], v[0:1], off
	global_load_dwordx4 v[18:21], v[2:3], off
	v_or_b32_e32 v0, 16, v52
	v_or_b32_e32 v2, 20, v52
	v_ashrrev_i32_e32 v1, 31, v0
	v_ashrrev_i32_e32 v3, 31, v2
	v_lshlrev_b64 v[0:1], 16, v[0:1]
	v_lshlrev_b64 v[2:3], 16, v[2:3]
	v_lshl_add_u64 v[0:1], v[50:51], 0, v[0:1]
	v_lshl_add_u64 v[2:3], v[50:51], 0, v[2:3]
	global_load_dwordx4 v[12:15], v[0:1], off
	global_load_dwordx4 v[8:11], v[2:3], off
	v_or_b32_e32 v0, 24, v52
	v_or_b32_e32 v2, 28, v52
	v_ashrrev_i32_e32 v1, 31, v0
	v_ashrrev_i32_e32 v3, 31, v2
	v_lshlrev_b64 v[0:1], 16, v[0:1]
	v_lshlrev_b64 v[2:3], 16, v[2:3]
	v_lshl_add_u64 v[0:1], v[50:51], 0, v[0:1]
	v_lshl_add_u64 v[2:3], v[50:51], 0, v[2:3]
	global_load_dwordx4 v[4:7], v[0:1], off
	s_nop 0
	global_load_dwordx4 v[0:3], v[2:3], off
	v_cndmask_b32_e64 v56, 0, 1, s[14:15]
	v_mov_b32_e32 v54, 1.0
	v_cmp_ne_u32_e64 s[4:5], 1, v56
	s_andn2_b64 vcc, exec, s[14:15]
	v_mov_b32_e32 v56, 1.0
	s_cbranch_vccnz .LBB0_817
	v_lshl_add_u64 v[86:87], v[52:53], 2, s[10:11]
	global_load_dword v110, v[86:87], off offset:16
	global_load_dword v124, v[86:87], off offset:32
	global_load_dword v125, v[86:87], off offset:48
	global_load_dword v126, v[86:87], off offset:64
	global_load_dword v127, v[86:87], off offset:80
	global_load_dword v178, v[86:87], off offset:96
	global_load_dword v179, v[86:87], off offset:112
	global_load_dword v180, v[86:87], off offset:128
	global_load_dword v181, v[86:87], off offset:144
	global_load_dword v182, v[86:87], off offset:160
	global_load_dword v183, v[86:87], off offset:176
	global_load_dword v184, v[86:87], off offset:192
	global_load_dword v185, v[86:87], off offset:208
	global_load_dword v186, v[86:87], off offset:224
	global_load_dword v187, v[86:87], off offset:240
	global_load_dword v56, v[86:87], off
	s_waitcnt vmcnt(0)
	s_ashr_i32 s19, s18, 31
	v_lshl_add_u64 v[86:87], s[18:19], 0, v[16:17]
	v_lshl_add_u64 v[86:87], v[86:87], 2, s[10:11]
	s_waitcnt vmcnt(0)
	v_pk_mul_f32 v[30:31], v[30:31], v[56:57] op_sel_hi:[1,0]
	v_pk_mul_f32 v[32:33], v[32:33], v[56:57] op_sel_hi:[1,0]
	v_mov_b32_e32 v56, v110
.LBB0_817:
	v_add_u32_e32 v53, v55, v57
	s_waitcnt vmcnt(7)
	ds_write2_b32 v53, v30, v31 offset1:1
	ds_write2_b32 v53, v32, v33 offset0:2 offset1:3
	s_waitcnt vmcnt(0)
	v_pk_mul_f32 v[26:27], v[26:27], v[56:57] op_sel_hi:[1,0]
	v_add_u32_e32 v30, 0x410, v53
	ds_write2_b32 v30, v26, v27 offset1:1
	v_pk_mul_f32 v[26:27], v[28:29], v[56:57] op_sel_hi:[1,0]
	v_add_u32_e32 v28, 0x418, v53
	s_and_b64 vcc, exec, s[4:5]
	ds_write2_b32 v28, v26, v27 offset1:1
	s_cbranch_vccnz .LBB0_819
	s_ashr_i32 s19, s18, 31
	v_lshl_add_u64 v[26:27], s[18:19], 0, v[16:17]
	v_lshl_add_u64 v[26:27], v[26:27], 2, s[10:11]
	v_mov_b32_e32 v28, v124
	v_mov_b32_e32 v54, v125
	s_waitcnt vmcnt(1)
	v_pk_mul_f32 v[22:23], v[22:23], v[28:29] op_sel_hi:[1,0]
	v_pk_mul_f32 v[24:25], v[24:25], v[28:29] op_sel_hi:[1,0]
.LBB0_819:
	ds_write2_b32 v83, v22, v23 offset1:1
	ds_write2_b32 v83, v24, v25 offset0:2 offset1:3
	s_waitcnt vmcnt(0)
	v_pk_mul_f32 v[18:19], v[18:19], v[54:55] op_sel_hi:[1,0]
	v_add_u32_e32 v22, 0x410, v83
	ds_write2_b32 v22, v18, v19 offset1:1
	v_pk_mul_f32 v[18:19], v[20:21], v[54:55] op_sel_hi:[1,0]
	v_add_u32_e32 v20, 0x418, v83
	ds_write2_b32 v20, v18, v19 offset1:1
	v_mov_b32_e32 v18, 1.0
	s_and_b64 vcc, exec, s[4:5]
	v_mov_b32_e32 v20, 1.0
	s_cbranch_vccnz .LBB0_821
	s_ashr_i32 s19, s18, 31
	v_lshl_add_u64 v[20:21], s[18:19], 0, v[16:17]
	v_lshl_add_u64 v[20:21], v[20:21], 2, s[10:11]
	v_mov_b32_e32 v22, v126
	s_waitcnt vmcnt(0)
	v_pk_mul_f32 v[12:13], v[12:13], v[22:23] op_sel_hi:[1,0]
	v_mov_b32_e32 v20, v127
	v_pk_mul_f32 v[14:15], v[14:15], v[22:23] op_sel_hi:[1,0]
; #define LAS __attribute__((address_space(3)))
; template <bool PERMUTE, bool BLOCKED = false>
; __device__ __forceinline__ void cvt_tile64(const float* W, int K, int N, bf16* WT, int ldo, const float* gk, LAS float* scr, int tile, int lane) {
;     ...
; #pragma unroll
;     for (int hh = 0; hh < 2; ++hh) {
;         f32x4 v[8];
; #pragma unroll
;         for (int i = 0; i < 8; ++i) v[i] = *(const f32x4*)(W + (size_t)(k0 + 32 * hh + 4 * i + lk) * N + n0 + ln);
; #pragma unroll
;         for (int i = 0; i < 8; ++i) { const int kk = 32 * hh + 4 * i + lk; const float g = gk ? gk[k0 + kk] : 1.0f; LAS float* d = scr + kk * 65 + ln;
;             d[0] = v[i][0] * g; d[1] = v[i][1] * g; d[2] = v[i][2] * g; d[3] = v[i][3] * g; }
;     }
.LBB0_821:
	ds_write2_b32 v84, v12, v13 offset1:1
	ds_write2_b32 v84, v14, v15 offset0:2 offset1:3
	s_waitcnt vmcnt(0)
	v_pk_mul_f32 v[8:9], v[8:9], v[20:21] op_sel_hi:[1,0]
	v_add_u32_e32 v12, 0x410, v84
	ds_write2_b32 v12, v8, v9 offset1:1
	v_pk_mul_f32 v[8:9], v[10:11], v[20:21] op_sel_hi:[1,0]
	v_add_u32_e32 v10, 0x418, v84
	s_and_b64 vcc, exec, s[4:5]
	ds_write2_b32 v10, v8, v9 offset1:1
	s_cbranch_vccnz .LBB0_823
	s_ashr_i32 s19, s18, 31
	v_lshl_add_u64 v[8:9], s[18:19], 0, v[16:17]
	v_lshl_add_u64 v[8:9], v[8:9], 2, s[10:11]
	v_mov_b32_e32 v10, v178
	v_mov_b32_e32 v18, v179
	s_waitcnt vmcnt(1)
	v_pk_mul_f32 v[4:5], v[4:5], v[10:11] op_sel_hi:[1,0]
	v_pk_mul_f32 v[6:7], v[6:7], v[10:11] op_sel_hi:[1,0]
.LBB0_823:
	v_add_u32_e32 v53, v55, v63
	v_add_u32_e32 v8, 0x410, v53
	ds_write2_b32 v8, v4, v5 offset1:1
	v_add_u32_e32 v4, 0x418, v53
	ds_write2_b32 v4, v6, v7 offset1:1
	s_waitcnt vmcnt(0)
	v_pk_mul_f32 v[0:1], v[0:1], v[18:19] op_sel_hi:[1,0]
	v_add_u32_e32 v4, 0x820, v53
	ds_write2_b32 v4, v0, v1 offset1:1
	v_pk_mul_f32 v[0:1], v[2:3], v[18:19] op_sel_hi:[1,0]
	v_add_u32_e32 v2, 0x828, v53
	ds_write2_b32 v2, v0, v1 offset1:1
	v_or_b32_e32 v0, 32, v52
	v_or_b32_e32 v4, 60, v52
	v_ashrrev_i32_e32 v1, 31, v0
	v_ashrrev_i32_e32 v5, 31, v4
	v_lshlrev_b64 v[0:1], 16, v[0:1]
	v_lshlrev_b64 v[4:5], 16, v[4:5]
	v_lshl_add_u64 v[0:1], v[50:51], 0, v[0:1]
	v_lshl_add_u64 v[4:5], v[50:51], 0, v[4:5]
	global_load_dwordx4 v[26:29], v[0:1], off
	s_and_b64 vcc, exec, s[4:5]
	global_load_dwordx4 v[4:7], v[4:5], off
	v_or_b32_e32 v0, 36, v52
	v_ashrrev_i32_e32 v1, 31, v0
	v_lshlrev_b64 v[0:1], 16, v[0:1]
	v_lshl_add_u64 v[0:1], v[50:51], 0, v[0:1]
	global_load_dwordx4 v[30:33], v[0:1], off
	v_or_b32_e32 v0, 40, v52
	v_ashrrev_i32_e32 v1, 31, v0
	v_lshlrev_b64 v[0:1], 16, v[0:1]
	v_lshl_add_u64 v[0:1], v[50:51], 0, v[0:1]
	global_load_dwordx4 v[18:21], v[0:1], off
	v_or_b32_e32 v0, 44, v52
	v_ashrrev_i32_e32 v1, 31, v0
	v_lshlrev_b64 v[0:1], 16, v[0:1]
	v_lshl_add_u64 v[0:1], v[50:51], 0, v[0:1]
	global_load_dwordx4 v[22:25], v[0:1], off
	v_or_b32_e32 v0, 48, v52
	v_ashrrev_i32_e32 v1, 31, v0
	v_lshlrev_b64 v[0:1], 16, v[0:1]
	v_lshl_add_u64 v[0:1], v[50:51], 0, v[0:1]
	global_load_dwordx4 v[8:11], v[0:1], off
	v_or_b32_e32 v0, 52, v52
	v_ashrrev_i32_e32 v1, 31, v0
	v_lshlrev_b64 v[0:1], 16, v[0:1]
	v_lshl_add_u64 v[0:1], v[50:51], 0, v[0:1]
	global_load_dwordx4 v[12:15], v[0:1], off
	v_or_b32_e32 v0, 56, v52
	v_ashrrev_i32_e32 v1, 31, v0
	v_lshlrev_b64 v[0:1], 16, v[0:1]
	v_lshl_add_u64 v[0:1], v[50:51], 0, v[0:1]
	global_load_dwordx4 v[0:3], v[0:1], off
	v_mov_b32_e32 v50, 1.0
	v_mov_b32_e32 v52, 1.0
	s_cbranch_vccnz .LBB0_825
	s_ashr_i32 s19, s18, 31
	v_lshl_add_u64 v[86:87], s[18:19], 0, v[16:17]
	v_lshl_add_u64 v[86:87], v[86:87], 2, s[10:11]
	v_mov_b32_e32 v52, v180
	s_waitcnt vmcnt(0)
	v_pk_mul_f32 v[26:27], v[26:27], v[52:53] op_sel_hi:[1,0]
	v_pk_mul_f32 v[28:29], v[28:29], v[52:53] op_sel_hi:[1,0]
	v_mov_b32_e32 v52, v181
.LBB0_825:
	v_add_u32_e32 v51, 0xc30, v53
	s_waitcnt vmcnt(7)
	ds_write2_b32 v51, v26, v27 offset1:1
	v_add_u32_e32 v26, 0xc38, v53
	ds_write2_b32 v26, v28, v29 offset1:1
	s_waitcnt vmcnt(0)
	v_pk_mul_f32 v[26:27], v[30:31], v[52:53] op_sel_hi:[1,0]
	v_add_u32_e32 v28, 0x1040, v53
	ds_write2_b32 v28, v26, v27 offset1:1
	v_pk_mul_f32 v[26:27], v[32:33], v[52:53] op_sel_hi:[1,0]
	v_add_u32_e32 v28, 0x1048, v53
	s_and_b64 vcc, exec, s[4:5]
	ds_write2_b32 v28, v26, v27 offset1:1
	s_cbranch_vccnz .LBB0_827
	s_ashr_i32 s19, s18, 31
	v_lshl_add_u64 v[26:27], s[18:19], 0, v[16:17]
	v_lshl_add_u64 v[26:27], v[26:27], 2, s[10:11]
	v_mov_b32_e32 v28, v182
	v_mov_b32_e32 v50, v183
	s_waitcnt vmcnt(1)
	v_pk_mul_f32 v[18:19], v[18:19], v[28:29] op_sel_hi:[1,0]
	v_pk_mul_f32 v[20:21], v[20:21], v[28:29] op_sel_hi:[1,0]
.LBB0_827:
	v_add_u32_e32 v26, 0x1450, v53
	ds_write2_b32 v26, v18, v19 offset1:1
	v_add_u32_e32 v18, 0x1458, v53
	ds_write2_b32 v18, v20, v21 offset1:1
	s_waitcnt vmcnt(0)
	v_pk_mul_f32 v[18:19], v[22:23], v[50:51] op_sel_hi:[1,0]
	v_add_u32_e32 v20, 0x1860, v53
	ds_write2_b32 v20, v18, v19 offset1:1
	v_pk_mul_f32 v[18:19], v[24:25], v[50:51] op_sel_hi:[1,0]
	v_add_u32_e32 v20, 0x1868, v53
	s_and_b64 vcc, exec, s[4:5]
	ds_write2_b32 v20, v18, v19 offset1:1
	s_cbranch_vccnz .LBB0_829
	s_ashr_i32 s19, s18, 31
	v_lshl_add_u64 v[18:19], s[18:19], 0, v[16:17]
	v_lshl_add_u64 v[18:19], v[18:19], 2, s[10:11]
	v_mov_b32_e32 v20, v184
	s_waitcnt vmcnt(0)
	v_pk_mul_f32 v[8:9], v[8:9], v[20:21] op_sel_hi:[1,0]
	v_mov_b32_e32 v18, v185
	v_pk_mul_f32 v[10:11], v[10:11], v[20:21] op_sel_hi:[1,0]
	s_branch .LBB0_830

; #define LAS __attribute__((address_space(3)))
; template <bool PERMUTE, bool BLOCKED = false>
; __device__ __forceinline__ void cvt_tile64(const float* W, int K, int N, bf16* WT, int ldo, const float* gk, LAS float* scr, int tile, int lane) {
;     ...
;         for (int i = 0; i < 8; ++i) { const int kk = 32 * hh + 4 * i + lk; const float g = gk ? gk[k0 + kk] : 1.0f; LAS float* d = scr + kk * 65 + ln;
;             d[0] = v[i][0] * g; d[1] = v[i][1] * g; d[2] = v[i][2] * g; d[3] = v[i][3] * g; }
;     }
.LBB0_830:
	v_add_u32_e32 v19, 0x1c70, v53
	ds_write2_b32 v19, v8, v9 offset1:1
	v_add_u32_e32 v8, 0x1c78, v53
	ds_write2_b32 v8, v10, v11 offset1:1
	s_waitcnt vmcnt(0)
	v_pk_mul_f32 v[8:9], v[12:13], v[18:19] op_sel_hi:[1,0]
	v_add_u32_e32 v10, 0x2080, v53
	ds_write2_b32 v10, v8, v9 offset1:1
	v_pk_mul_f32 v[8:9], v[14:15], v[18:19] op_sel_hi:[1,0]
	v_add_u32_e32 v10, 0x2088, v53
	s_and_b64 vcc, exec, s[14:15]
	ds_write2_b32 v10, v8, v9 offset1:1
	s_cbranch_vccz .LBB0_837
	s_ashr_i32 s19, s18, 31
	v_lshl_add_u64 v[8:9], s[18:19], 0, v[16:17]
	v_lshl_add_u64 v[8:9], v[8:9], 2, s[10:11]
	v_mov_b32_e32 v10, v186
	s_nop 0
	v_mov_b32_e32 v8, v187
	s_waitcnt vmcnt(1)
	v_pk_mul_f32 v[0:1], v[0:1], v[10:11] op_sel_hi:[1,0]
	v_pk_mul_f32 v[2:3], v[2:3], v[10:11] op_sel_hi:[1,0]
	s_cbranch_execnz .LBB0_833

; #define LAS __attribute__((address_space(3)))
; template <bool PERMUTE, bool BLOCKED = false>
; __device__ __forceinline__ void cvt_tile64(const float* W, int K, int N, bf16* WT, int ldo, const float* gk, LAS float* scr, int tile, int lane) {
;     const int nblk = N >> 6, kb = tile / nblk, nb = tile - kb * nblk, k0 = 64 * kb, n0 = 64 * nb;
;     const int lk = lane >> 4, ln = (lane & 15) * 4;
;     ...
;     {
;         f32x4 v[16];
; #pragma unroll
;         for (int i = 0; i < 16; ++i) v[i] = *(const f32x4*)(W + (size_t)(k0 + 4 * i + lk) * N + n0 + ln);
; #pragma unroll
;         for (int i = 0; i < 16; ++i) { const int kk = 4 * i + lk; const float g = gk ? gk[k0 + kk] : 1.0f; LAS float* d = scr + kk * 65 + ln;
;             d[0] = v[i][0] * g; d[1] = v[i][1] * g; d[2] = v[i][2] * g; d[3] = v[i][3] * g; }
;     }
;     ...
; #pragma unroll
;     for (int hh = 0; hh < 2; ++hh) {
;         f32x4 v[8];
; #pragma unroll
;         for (int i = 0; i < 8; ++i) v[i] = *(const f32x4*)(W + (size_t)(k0 + 32 * hh + 4 * i + lk) * N + n0 + ln);
; #pragma unroll
;         for (int i = 0; i < 8; ++i) { const int kk = 32 * hh + 4 * i + lk; const float g = gk ? gk[k0 + kk] : 1.0f; LAS float* d = scr + kk * 65 + ln;
;             d[0] = v[i][0] * g; d[1] = v[i][1] * g; d[2] = v[i][2] * g; d[3] = v[i][3] * g; }
;     }
; __device__ __forceinline__ void cvt_item(const CvtCtx& c, int batch, int wi, LAS float* scr, int wave, int lane) {
;     ...
;     if (wi < CVT_OUT) { cvt_tile64<false>(c.w_out + (size_t)l * DM * DM, DM, DM, c.WoutT + (size_t)l * DM * DM, DM, nullptr, scr, 8 * wi + wave, lane); return; } wi -= CVT_OUT;
;     if (wi < CVT_UP) { cvt_tile64<false>(c.w_up + (size_t)l * DM * DFF, DM, DFF, c.WupT + (size_t)l * DFF * DM, DM, c.g_mlp + l * DM, scr, 8 * wi + wave, lane); return; } wi -= CVT_UP;
.LBB0_882:
	s_andn2_b64 vcc, exec, s[0:1]
	s_cbranch_vccnz .LBB0_902
	s_add_i32 s0, s16, 0x8000
	s_ashr_i32 s1, s0, 31
	s_lshr_b32 s1, s1, 24
	s_add_i32 s0, s0, s1
	s_ashr_i32 s0, s0, 8
	s_lshl_b32 s10, s0, 6
	s_lshl_b32 s18, s0, 14
	s_sub_i32 s0, s15, s18
	v_or_b32_e32 v52, s10, v16
	s_add_i32 s0, s0, 0x200000
	v_or_b32_e32 v2, 4, v52
	s_ashr_i32 s1, s0, 31
	v_ashrrev_i32_e32 v53, 31, v52
	v_ashrrev_i32_e32 v3, 31, v2
	v_lshl_add_u64 v[50:51], s[0:1], 2, v[42:43]
	v_lshlrev_b64 v[0:1], 16, v[52:53]
	v_lshlrev_b64 v[2:3], 16, v[2:3]
	v_lshl_add_u64 v[0:1], v[50:51], 0, v[0:1]
	v_lshl_add_u64 v[2:3], v[50:51], 0, v[2:3]
	global_load_dwordx4 v[30:33], v[0:1], off
	global_load_dwordx4 v[26:29], v[2:3], off
	v_or_b32_e32 v0, 8, v52
	v_or_b32_e32 v2, 12, v52
	v_ashrrev_i32_e32 v1, 31, v0
	v_ashrrev_i32_e32 v3, 31, v2
	v_lshlrev_b64 v[0:1], 16, v[0:1]
	v_lshlrev_b64 v[2:3], 16, v[2:3]
	v_lshl_add_u64 v[0:1], v[50:51], 0, v[0:1]
	v_lshl_add_u64 v[2:3], v[50:51], 0, v[2:3]
	global_load_dwordx4 v[22:25], v[0:1], off
	global_load_dwordx4 v[18:21], v[2:3], off
	v_or_b32_e32 v0, 16, v52
	v_or_b32_e32 v2, 20, v52
	v_ashrrev_i32_e32 v1, 31, v0
	v_ashrrev_i32_e32 v3, 31, v2
	v_lshlrev_b64 v[0:1], 16, v[0:1]
	v_lshlrev_b64 v[2:3], 16, v[2:3]
	v_lshl_add_u64 v[0:1], v[50:51], 0, v[0:1]
	v_lshl_add_u64 v[2:3], v[50:51], 0, v[2:3]
	global_load_dwordx4 v[12:15], v[0:1], off
	global_load_dwordx4 v[8:11], v[2:3], off
	v_or_b32_e32 v0, 24, v52
	v_or_b32_e32 v2, 28, v52
	v_ashrrev_i32_e32 v1, 31, v0
	v_ashrrev_i32_e32 v3, 31, v2
	v_lshlrev_b64 v[0:1], 16, v[0:1]
	v_lshlrev_b64 v[2:3], 16, v[2:3]
	v_lshl_add_u64 v[0:1], v[50:51], 0, v[0:1]
	v_lshl_add_u64 v[2:3], v[50:51], 0, v[2:3]
	global_load_dwordx4 v[4:7], v[0:1], off
	s_nop 0
	global_load_dwordx4 v[0:3], v[2:3], off
	v_cndmask_b32_e64 v56, 0, 1, s[6:7]
	v_mov_b32_e32 v54, 1.0
	v_cmp_ne_u32_e64 s[4:5], 1, v56
	s_andn2_b64 vcc, exec, s[6:7]
	v_mov_b32_e32 v56, 1.0
	s_cbranch_vccnz .LBB0_885
	v_lshl_add_u64 v[86:87], v[52:53], 2, s[8:9]
	global_load_dword v110, v[86:87], off offset:16
	global_load_dword v124, v[86:87], off offset:32
	global_load_dword v125, v[86:87], off offset:48
	global_load_dword v126, v[86:87], off offset:64
	global_load_dword v127, v[86:87], off offset:80
	global_load_dword v178, v[86:87], off offset:96
	global_load_dword v179, v[86:87], off offset:112
	global_load_dword v180, v[86:87], off offset:128
	global_load_dword v181, v[86:87], off offset:144
	global_load_dword v182, v[86:87], off offset:160
	global_load_dword v183, v[86:87], off offset:176
	global_load_dword v184, v[86:87], off offset:192
	global_load_dword v185, v[86:87], off offset:208
	global_load_dword v186, v[86:87], off offset:224
	global_load_dword v187, v[86:87], off offset:240
	global_load_dword v56, v[86:87], off
	s_waitcnt vmcnt(0)
	s_ashr_i32 s11, s10, 31
	v_lshl_add_u64 v[86:87], s[10:11], 0, v[16:17]
	v_lshl_add_u64 v[86:87], v[86:87], 2, s[8:9]
	s_waitcnt vmcnt(0)
	v_pk_mul_f32 v[30:31], v[30:31], v[56:57] op_sel_hi:[1,0]
	v_pk_mul_f32 v[32:33], v[32:33], v[56:57] op_sel_hi:[1,0]
	v_mov_b32_e32 v56, v110
.LBB0_885:
	v_add_u32_e32 v53, v55, v57
	s_waitcnt vmcnt(7)
	ds_write2_b32 v53, v30, v31 offset1:1
	ds_write2_b32 v53, v32, v33 offset0:2 offset1:3
	s_waitcnt vmcnt(0)
	v_pk_mul_f32 v[26:27], v[26:27], v[56:57] op_sel_hi:[1,0]
	v_add_u32_e32 v30, 0x410, v53
	ds_write2_b32 v30, v26, v27 offset1:1
	v_pk_mul_f32 v[26:27], v[28:29], v[56:57] op_sel_hi:[1,0]
	v_add_u32_e32 v28, 0x418, v53
	s_and_b64 vcc, exec, s[4:5]
	ds_write2_b32 v28, v26, v27 offset1:1
	s_cbranch_vccnz .LBB0_887
	s_ashr_i32 s11, s10, 31
	v_lshl_add_u64 v[26:27], s[10:11], 0, v[16:17]
	v_lshl_add_u64 v[26:27], v[26:27], 2, s[8:9]
	v_mov_b32_e32 v28, v124
	v_mov_b32_e32 v54, v125
	s_waitcnt vmcnt(1)
	v_pk_mul_f32 v[22:23], v[22:23], v[28:29] op_sel_hi:[1,0]
	v_pk_mul_f32 v[24:25], v[24:25], v[28:29] op_sel_hi:[1,0]
.LBB0_887:
	ds_write2_b32 v83, v22, v23 offset1:1
	ds_write2_b32 v83, v24, v25 offset0:2 offset1:3
	s_waitcnt vmcnt(0)
	v_pk_mul_f32 v[18:19], v[18:19], v[54:55] op_sel_hi:[1,0]
	v_add_u32_e32 v22, 0x410, v83
	ds_write2_b32 v22, v18, v19 offset1:1
	v_pk_mul_f32 v[18:19], v[20:21], v[54:55] op_sel_hi:[1,0]
	v_add_u32_e32 v20, 0x418, v83
	ds_write2_b32 v20, v18, v19 offset1:1
	v_mov_b32_e32 v18, 1.0
	s_and_b64 vcc, exec, s[4:5]
	v_mov_b32_e32 v20, 1.0
	s_cbranch_vccnz .LBB0_889
	s_ashr_i32 s11, s10, 31
	v_lshl_add_u64 v[20:21], s[10:11], 0, v[16:17]
	v_lshl_add_u64 v[20:21], v[20:21], 2, s[8:9]
	v_mov_b32_e32 v22, v126
	s_waitcnt vmcnt(0)
	v_pk_mul_f32 v[12:13], v[12:13], v[22:23] op_sel_hi:[1,0]
	v_mov_b32_e32 v20, v127
	v_pk_mul_f32 v[14:15], v[14:15], v[22:23] op_sel_hi:[1,0]
; #define LAS __attribute__((address_space(3)))
; template <bool PERMUTE, bool BLOCKED = false>
; __device__ __forceinline__ void cvt_tile64(const float* W, int K, int N, bf16* WT, int ldo, const float* gk, LAS float* scr, int tile, int lane) {
;     ...
; #pragma unroll
;     for (int hh = 0; hh < 2; ++hh) {
;         f32x4 v[8];
; #pragma unroll
;         for (int i = 0; i < 8; ++i) v[i] = *(const f32x4*)(W + (size_t)(k0 + 32 * hh + 4 * i + lk) * N + n0 + ln);
; #pragma unroll
;         for (int i = 0; i < 8; ++i) { const int kk = 32 * hh + 4 * i + lk; const float g = gk ? gk[k0 + kk] : 1.0f; LAS float* d = scr + kk * 65 + ln;
;             d[0] = v[i][0] * g; d[1] = v[i][1] * g; d[2] = v[i][2] * g; d[3] = v[i][3] * g; }
;     }
.LBB0_889:
	ds_write2_b32 v84, v12, v13 offset1:1
	ds_write2_b32 v84, v14, v15 offset0:2 offset1:3
	s_waitcnt vmcnt(0)
	v_pk_mul_f32 v[8:9], v[8:9], v[20:21] op_sel_hi:[1,0]
	v_add_u32_e32 v12, 0x410, v84
	ds_write2_b32 v12, v8, v9 offset1:1
	v_pk_mul_f32 v[8:9], v[10:11], v[20:21] op_sel_hi:[1,0]
	v_add_u32_e32 v10, 0x418, v84
	s_and_b64 vcc, exec, s[4:5]
	ds_write2_b32 v10, v8, v9 offset1:1
	s_cbranch_vccnz .LBB0_891
	s_ashr_i32 s11, s10, 31
	v_lshl_add_u64 v[8:9], s[10:11], 0, v[16:17]
	v_lshl_add_u64 v[8:9], v[8:9], 2, s[8:9]
	v_mov_b32_e32 v10, v178
	v_mov_b32_e32 v18, v179
	s_waitcnt vmcnt(1)
	v_pk_mul_f32 v[4:5], v[4:5], v[10:11] op_sel_hi:[1,0]
	v_pk_mul_f32 v[6:7], v[6:7], v[10:11] op_sel_hi:[1,0]
.LBB0_891:
	v_add_u32_e32 v53, v55, v63
	v_add_u32_e32 v8, 0x410, v53
	ds_write2_b32 v8, v4, v5 offset1:1
	v_add_u32_e32 v4, 0x418, v53
	ds_write2_b32 v4, v6, v7 offset1:1
	s_waitcnt vmcnt(0)
	v_pk_mul_f32 v[0:1], v[0:1], v[18:19] op_sel_hi:[1,0]
	v_add_u32_e32 v4, 0x820, v53
	ds_write2_b32 v4, v0, v1 offset1:1
	v_pk_mul_f32 v[0:1], v[2:3], v[18:19] op_sel_hi:[1,0]
	v_add_u32_e32 v2, 0x828, v53
	ds_write2_b32 v2, v0, v1 offset1:1
	v_or_b32_e32 v0, 32, v52
	v_or_b32_e32 v4, 60, v52
	v_ashrrev_i32_e32 v1, 31, v0
	v_ashrrev_i32_e32 v5, 31, v4
	v_lshlrev_b64 v[0:1], 16, v[0:1]
	v_lshlrev_b64 v[4:5], 16, v[4:5]
	v_lshl_add_u64 v[0:1], v[50:51], 0, v[0:1]
	v_lshl_add_u64 v[4:5], v[50:51], 0, v[4:5]
	global_load_dwordx4 v[26:29], v[0:1], off
	s_and_b64 vcc, exec, s[4:5]
	global_load_dwordx4 v[4:7], v[4:5], off
	v_or_b32_e32 v0, 36, v52
	v_ashrrev_i32_e32 v1, 31, v0
	v_lshlrev_b64 v[0:1], 16, v[0:1]
	v_lshl_add_u64 v[0:1], v[50:51], 0, v[0:1]
	global_load_dwordx4 v[30:33], v[0:1], off
	v_or_b32_e32 v0, 40, v52
	v_ashrrev_i32_e32 v1, 31, v0
	v_lshlrev_b64 v[0:1], 16, v[0:1]
	v_lshl_add_u64 v[0:1], v[50:51], 0, v[0:1]
	global_load_dwordx4 v[18:21], v[0:1], off
	v_or_b32_e32 v0, 44, v52
	v_ashrrev_i32_e32 v1, 31, v0
	v_lshlrev_b64 v[0:1], 16, v[0:1]
	v_lshl_add_u64 v[0:1], v[50:51], 0, v[0:1]
	global_load_dwordx4 v[22:25], v[0:1], off
	v_or_b32_e32 v0, 48, v52
	v_ashrrev_i32_e32 v1, 31, v0
	v_lshlrev_b64 v[0:1], 16, v[0:1]
	v_lshl_add_u64 v[0:1], v[50:51], 0, v[0:1]
	global_load_dwordx4 v[8:11], v[0:1], off
	v_or_b32_e32 v0, 52, v52
	v_ashrrev_i32_e32 v1, 31, v0
	v_lshlrev_b64 v[0:1], 16, v[0:1]
	v_lshl_add_u64 v[0:1], v[50:51], 0, v[0:1]
	global_load_dwordx4 v[12:15], v[0:1], off
	v_or_b32_e32 v0, 56, v52
	v_ashrrev_i32_e32 v1, 31, v0
	v_lshlrev_b64 v[0:1], 16, v[0:1]
	v_lshl_add_u64 v[0:1], v[50:51], 0, v[0:1]
	global_load_dwordx4 v[0:3], v[0:1], off
	v_mov_b32_e32 v50, 1.0
	v_mov_b32_e32 v52, 1.0
	s_cbranch_vccnz .LBB0_893
	s_ashr_i32 s11, s10, 31
	v_lshl_add_u64 v[86:87], s[10:11], 0, v[16:17]
	v_lshl_add_u64 v[86:87], v[86:87], 2, s[8:9]
	v_mov_b32_e32 v52, v180
	s_waitcnt vmcnt(0)
	v_pk_mul_f32 v[26:27], v[26:27], v[52:53] op_sel_hi:[1,0]
	v_pk_mul_f32 v[28:29], v[28:29], v[52:53] op_sel_hi:[1,0]
	v_mov_b32_e32 v52, v181
.LBB0_893:
	v_add_u32_e32 v51, 0xc30, v53
	s_waitcnt vmcnt(7)
	ds_write2_b32 v51, v26, v27 offset1:1
	v_add_u32_e32 v26, 0xc38, v53
	ds_write2_b32 v26, v28, v29 offset1:1
	s_waitcnt vmcnt(0)
	v_pk_mul_f32 v[26:27], v[30:31], v[52:53] op_sel_hi:[1,0]
	v_add_u32_e32 v28, 0x1040, v53
	ds_write2_b32 v28, v26, v27 offset1:1
	v_pk_mul_f32 v[26:27], v[32:33], v[52:53] op_sel_hi:[1,0]
	v_add_u32_e32 v28, 0x1048, v53
	s_and_b64 vcc, exec, s[4:5]
	ds_write2_b32 v28, v26, v27 offset1:1
	s_cbranch_vccnz .LBB0_895
	s_ashr_i32 s11, s10, 31
	v_lshl_add_u64 v[26:27], s[10:11], 0, v[16:17]
	v_lshl_add_u64 v[26:27], v[26:27], 2, s[8:9]
	v_mov_b32_e32 v28, v182
	v_mov_b32_e32 v50, v183
	s_waitcnt vmcnt(1)
	v_pk_mul_f32 v[18:19], v[18:19], v[28:29] op_sel_hi:[1,0]
	v_pk_mul_f32 v[20:21], v[20:21], v[28:29] op_sel_hi:[1,0]
.LBB0_895:
	v_add_u32_e32 v26, 0x1450, v53
	ds_write2_b32 v26, v18, v19 offset1:1
	v_add_u32_e32 v18, 0x1458, v53
	ds_write2_b32 v18, v20, v21 offset1:1
	s_waitcnt vmcnt(0)
	v_pk_mul_f32 v[18:19], v[22:23], v[50:51] op_sel_hi:[1,0]
	v_add_u32_e32 v20, 0x1860, v53
	ds_write2_b32 v20, v18, v19 offset1:1
	v_pk_mul_f32 v[18:19], v[24:25], v[50:51] op_sel_hi:[1,0]
	v_add_u32_e32 v20, 0x1868, v53
	s_and_b64 vcc, exec, s[4:5]
	ds_write2_b32 v20, v18, v19 offset1:1
	s_cbranch_vccnz .LBB0_897
	s_ashr_i32 s11, s10, 31
	v_lshl_add_u64 v[18:19], s[10:11], 0, v[16:17]
	v_lshl_add_u64 v[18:19], v[18:19], 2, s[8:9]
	v_mov_b32_e32 v20, v184
	s_waitcnt vmcnt(0)
	v_pk_mul_f32 v[8:9], v[8:9], v[20:21] op_sel_hi:[1,0]
	v_mov_b32_e32 v18, v185
	v_pk_mul_f32 v[10:11], v[10:11], v[20:21] op_sel_hi:[1,0]
	s_branch .LBB0_898

; #define LAS __attribute__((address_space(3)))
; template <bool PERMUTE, bool BLOCKED = false>
; __device__ __forceinline__ void cvt_tile64(const float* W, int K, int N, bf16* WT, int ldo, const float* gk, LAS float* scr, int tile, int lane) {
;     ...
;         for (int i = 0; i < 8; ++i) { const int kk = 32 * hh + 4 * i + lk; const float g = gk ? gk[k0 + kk] : 1.0f; LAS float* d = scr + kk * 65 + ln;
;             d[0] = v[i][0] * g; d[1] = v[i][1] * g; d[2] = v[i][2] * g; d[3] = v[i][3] * g; }
;     }
.LBB0_898:
	v_add_u32_e32 v19, 0x1c70, v53
	ds_write2_b32 v19, v8, v9 offset1:1
	v_add_u32_e32 v8, 0x1c78, v53
	ds_write2_b32 v8, v10, v11 offset1:1
	s_waitcnt vmcnt(0)
	v_pk_mul_f32 v[8:9], v[12:13], v[18:19] op_sel_hi:[1,0]
	v_add_u32_e32 v10, 0x2080, v53
	ds_write2_b32 v10, v8, v9 offset1:1
	v_pk_mul_f32 v[8:9], v[14:15], v[18:19] op_sel_hi:[1,0]
	v_add_u32_e32 v10, 0x2088, v53
	s_and_b64 vcc, exec, s[6:7]
	ds_write2_b32 v10, v8, v9 offset1:1
	s_cbranch_vccz .LBB0_905
	s_ashr_i32 s11, s10, 31
	v_lshl_add_u64 v[8:9], s[10:11], 0, v[16:17]
	v_lshl_add_u64 v[8:9], v[8:9], 2, s[8:9]
	v_mov_b32_e32 v10, v186
	s_nop 0
	v_mov_b32_e32 v8, v187
	s_waitcnt vmcnt(1)
	v_pk_mul_f32 v[0:1], v[0:1], v[10:11] op_sel_hi:[1,0]
	v_pk_mul_f32 v[2:3], v[2:3], v[10:11] op_sel_hi:[1,0]
	s_cbranch_execnz .LBB0_901
